# SG and FFT1 outputs (and SG u inputs) also staged through LDS as whole 256-B row segments
# speedup vs baseline: 1.0120x; 1.0120x over previous
; __device__ __forceinline__ int otid(int wv) { int t; asm volatile("v_mbcnt_lo_u32_b32 %0, -1, 0\n\tv_mbcnt_hi_u32_b32 %0, -1, %0\n\tv_lshl_add_u32 %0, %1, 6, %0" : "=&v"(t) : "s"(wv)); return t; }
; __device__ __forceinline__ unsigned cvt_pk_bf16(float lo, float hi) { const f2_t v = {lo, hi}; const bf2_t b = __builtin_convertvector(v, bf2_t); return __builtin_bit_cast(unsigned, b); }
; __device__ void sg_phase(int wv, const Params& p, int jl, unsigned char* lds) {
;     const int tid = otid(wv), lane = tid & 63, w = __builtin_amdgcn_readfirstlane(tid >> 6), lr = lane & 15, lq = lane >> 4;
;     bf16_t* uv = (bf16_t*)(p.ws + WS_BIG1);
;     const u64* vss = (const u64*)(p.ws + WS_SS) + (size_t)(9 + jl) * MTOK;
;     constexpr int PW = 136;
;     bf16_t* WsL = (bf16_t*)lds; bf16_t* VTL = WsL + 128 * PW; float* rsL = (float*)(VTL + 128 * PW);
;     for (int unit = blockIdx.x; unit < 2048; unit += gridDim.x) {
;         const int ch = unit >> 3, g = unit & 7, t0 = ch * 128;
;         if (tid < 128) rsL[tid] = 1.0f / sqrtf((float)vss[t0 + tid] * SSKI + EPSN);
;         __syncthreads();
;         const float* ws = p.a_w_s + ((size_t)jl * 8 + g) * 128 * 128;
; #pragma unroll
;         for (int ps = 0; ps < 8; ++ps) { const int idx = tid + ps * NTHR, t = idx >> 5, s4 = (idx & 31) * 4;
;             const f32x4 wv = *(const f32x4*)(ws + t * 128 + s4); const f32x4 r4 = *(const f32x4*)(rsL + s4); const f32x4 x = wv * r4;
;             u32x2 pk; pk.x = cvt_pk_bf16(x[0], x[1]); pk.y = cvt_pk_bf16(x[2], x[3]); *(u32x2*)(WsL + t * PW + s4) = pk; }
; #pragma unroll
;         for (int ps = 0; ps < 4; ++ps) { const int idx = tid + ps * NTHR, s = idx & 127, d8 = (idx >> 7) * 8;
;             const bf16x8 v = *(const bf16x8*)(uv + (size_t)(t0 + s) * 2048 + 1024 + g * 128 + d8);
; #pragma unroll
;             for (int e = 0; e < 8; ++e) VTL[(d8 + e) * PW + s] = (bf16_t)v[e]; }
;         __syncthreads();
;         bf16x8 af[4];
; #pragma unroll
;         for (int kk = 0; kk < 4; ++kk) af[kk] = *(const bf16x8*)(WsL + (16 * w + lr) * PW + 32 * kk + 8 * lq);
;         const int tok = t0 + 16 * w + lr; const float bs = p.a_b_s[((size_t)jl * 8 + g) * 128 + 16 * w + lr];
.LBB0_284:
	s_andn2_b64 vcc, exec, s[74:75]
	s_cbranch_vccnz .LBB0_290
	v_readlane_b32 s4, v254, 9
	v_readlane_b32 s5, v254, 10
	v_mbcnt_lo_u32_b32 v1, -1, 0
	v_mbcnt_hi_u32_b32 v1, -1, v1
	v_lshl_add_u32 v1, s33, 6, v1
	s_andn2_b64 vcc, exec, s[4:5]
	v_readfirstlane_b32 s6, v1
	s_cbranch_vccnz .LBB0_290
	s_and_b64 s[4:5], s[8:9], exec
	s_mov_b32 s4, 0x280000
	s_cselect_b32 s4, s4, 0x240000
	s_add_u32 s10, s30, s4
	s_addc_u32 s11, s31, 0
	s_and_b64 s[14:15], s[8:9], exec
	v_add_u32_e32 v30, 0xc00, v1
	v_bfe_u32 v3, v1, 4, 2
	s_movk_i32 s14, 0x110
	v_ashrrev_i32_e32 v32, 5, v30
	v_lshlrev_b32_e32 v8, 4, v3
	v_lshlrev_b32_e32 v53, 2, v3
	v_ashrrev_i32_e32 v3, 5, v1
	v_lshlrev_b32_e32 v30, 7, v32
	v_mul_lo_u32 v46, v32, s14
	v_add_u32_e32 v32, 0xe00, v1
	v_lshlrev_b32_e32 v2, 2, v1
	v_lshlrev_b32_e32 v18, 7, v3
	v_mul_lo_u32 v10, v3, s14
	v_add_u32_e32 v3, 0x200, v1
	v_ashrrev_i32_e32 v34, 5, v32
	v_ashrrev_i32_e32 v36, 4, v1
	v_readlane_b32 s7, v254, 57
	v_and_b32_e32 v5, 0x7c, v2
	v_ashrrev_i32_e32 v11, 5, v3
	v_lshlrev_b32_e32 v32, 7, v34
	v_mul_lo_u32 v48, v34, s14
	v_and_b32_e32 v34, -8, v36
	v_or_b32_e32 v36, 7, v36
	v_ashrrev_i32_e32 v3, 4, v3
	v_add_u32_e32 v47, s7, v2
	v_lshlrev_b32_e32 v2, 2, v5
	v_add_u32_e32 v12, 0x400, v1
	v_mul_lo_u32 v63, v36, s14
	v_and_b32_e32 v36, -8, v3
	v_or_b32_e32 v3, 7, v3
	s_cselect_b32 s20, 0x400, 0
	v_add_u32_e32 v50, s7, v2
	s_ashr_i32 s7, s6, 2
	v_mul_lo_u32 v65, v3, s14
	v_ashrrev_i32_e32 v3, 4, v12
	s_and_b32 s6, s7, -16
	v_add_u32_e32 v14, 0x600, v1
	v_and_b32_e32 v38, -8, v3
	v_or_b32_e32 v3, 7, v3
	v_bfi_b32 v52, -16, s7, v1
	s_ashr_i32 s7, s6, 31
	v_mul_lo_u32 v67, v3, s14
	v_ashrrev_i32_e32 v3, 4, v14
	v_and_b32_e32 v40, -8, v3
	v_or_b32_e32 v3, 7, v3
	s_lshl_b64 s[6:7], s[6:7], 2
	v_and_b32_e32 v4, 15, v1
	v_mul_lo_u32 v69, v3, s14
	v_mov_b32_e32 v3, v0
	s_add_u32 s6, s52, s6
	v_add_u32_e32 v16, 0x800, v1
	v_add_u32_e32 v17, 0xa00, v1
	v_lshl_add_u64 v[42:43], s[50:51], 0, v[2:3]
	s_addc_u32 s7, s53, s7
	v_lshlrev_b32_e32 v2, 2, v4
	v_and_b32_e32 v51, 0x7f, v1
	v_mul_lo_u32 v7, v52, s14
	v_ashrrev_i32_e32 v13, 5, v12
	v_ashrrev_i32_e32 v15, 5, v14
	v_ashrrev_i32_e32 v16, 5, v16
	v_ashrrev_i32_e32 v17, 5, v17
	v_lshl_add_u64 v[44:45], s[6:7], 0, v[2:3]
	s_lshl_b32 s6, s20, 2
	s_movk_i32 s4, 0x80
	v_lshl_add_u32 v5, v5, 1, 0
	v_lshl_add_u32 v6, v51, 1, 0
	v_add_u32_e32 v7, 0, v7
	v_add_u32_e32 v9, 0, v8
	v_lshlrev_b32_e32 v20, 7, v11
	v_mul_lo_u32 v11, v11, s14
	v_lshlrev_b32_e32 v22, 7, v13
	v_mul_lo_u32 v13, v13, s14
	v_lshlrev_b32_e32 v24, 7, v15
	v_mul_lo_u32 v15, v15, s14
	v_lshlrev_b32_e32 v26, 7, v16
	v_mul_lo_u32 v16, v16, s14
	v_lshlrev_b32_e32 v28, 7, v17
	v_mul_lo_u32 v17, v17, s14
	v_mul_lo_u32 v49, v34, s14
	v_mul_lo_u32 v64, v36, s14
	v_mul_lo_u32 v12, v38, s14
	v_mul_lo_u32 v14, v40, s14
	v_mul_u32_u24_e32 v71, 0x110, v4
	s_add_u32 s14, s48, s6
	v_cmp_gt_i32_e64 s[4:5], s4, v1
	v_ashrrev_i32_e32 v19, 31, v18
	v_ashrrev_i32_e32 v21, 31, v20
	v_ashrrev_i32_e32 v23, 31, v22
	v_ashrrev_i32_e32 v25, 31, v24
	v_ashrrev_i32_e32 v27, 31, v26
	v_ashrrev_i32_e32 v29, 31, v28
	v_ashrrev_i32_e32 v31, 31, v30
	v_ashrrev_i32_e32 v33, 31, v32
	v_ashrrev_i32_e32 v35, 31, v34
	v_ashrrev_i32_e32 v37, 31, v36
	v_ashrrev_i32_e32 v39, 31, v38
	v_ashrrev_i32_e32 v41, 31, v40
	s_addc_u32 s15, s49, 0
	v_add_u32_e32 v54, v5, v10
	v_add_u32_e32 v55, v5, v11
	v_add_u32_e32 v56, v5, v13
	v_add_u32_e32 v57, v5, v15
	v_add_u32_e32 v58, v5, v16
	v_add_u32_e32 v59, v5, v17
	v_add_u32_e32 v60, v5, v46
	v_add_u32_e32 v61, v5, v48
	v_add_u32_e32 v62, v6, v49
	v_add_u32_e32 v63, v6, v63
	v_add_u32_e32 v64, v6, v64
	v_add_u32_e32 v65, v6, v65
	v_add_u32_e32 v66, v6, v12
	v_add_u32_e32 v67, v6, v67
	v_add_u32_e32 v68, v6, v14
	v_add_u32_e32 v69, v6, v69
	v_add_u32_e32 v70, v7, v8
	v_add_u32_e32 v71, v9, v71
	v_readlane_b32 s21, v254, 41
	v_readlane_b32 s22, v254, 40
	s_mov_b32 s23, s2
	v_mbcnt_lo_u32_b32 v222, -1, 0
	v_mbcnt_hi_u32_b32 v222, -1, v222
	v_lshl_add_u32 v223, s33, 6, v222
	v_lshrrev_b32_e32 v224, 4, v223
	v_and_b32_e32 v225, 15, v223
	v_and_b32_e32 v226, 3, v224
	v_lshlrev_b32_e32 v226, 2, v226
	v_bfe_u32 v227, v224, 2, 2
	v_or_b32_e32 v226, v226, v227
	v_xor_b32_e32 v226, v225, v226
	v_lshlrev_b32_e32 v226, 4, v226
	v_lshl_add_u32 v212, v224, 8, v226
	v_add_u32_e32 v212, 0x8800, v212
	v_lshlrev_b32_e32 v214, 12, v224
	v_lshl_add_u32 v214, v225, 4, v214
	v_mov_b32_e32 v215, 0
	v_lshl_add_u64 v[214:215], s[76:77], 0, v[214:215]
	v_bfe_u32 v224, v222, 2, 2
	v_and_b32_e32 v225, 3, v222
	v_lshrrev_b32_e32 v226, 4, v222
	v_lshl_add_u32 v227, v226, 3, v224
	v_lshlrev_b32_e32 v228, 2, v224
	v_lshlrev_b32_e32 v226, 1, v226
	v_and_b32_e32 v229, 3, v226
	v_or_b32_e32 v229, v228, v229
	v_add_u32_e32 v226, 1, v226
	v_and_b32_e32 v226, 3, v226
	v_or_b32_e32 v226, v228, v226
	v_lshrrev_b32_e32 v228, 1, v225
	v_and_b32_e32 v225, 1, v225
	v_lshlrev_b32_e32 v225, 3, v225
	v_xor_b32_e32 v229, v228, v229
	v_lshl_add_u32 v229, v229, 4, v225
	v_lshl_add_u32 v218, v227, 8, v229
	v_add_u32_e32 v218, 0x8800, v218
	v_xor_b32_e32 v226, v228, v226
	v_lshl_add_u32 v226, v226, 4, v225
	v_add_u32_e32 v227, 4, v227
	v_lshl_add_u32 v219, v227, 8, v226
	v_add_u32_e32 v219, 0x8800, v219
	v_lshrrev_b32_e32 v213, 4, v223
	v_mul_u32_u24_e32 v213, 0x110, v213
	v_and_b32_e32 v216, 15, v223
	v_lshl_add_u32 v213, v216, 4, v213
	v_add_u32_e32 v213, 0x11400, v213
	v_and_b32_e32 v216, 15, v222
	s_lshl_b32 s6, s33, 4
	v_add_u32_e32 v216, s6, v216
	v_mul_u32_u24_e32 v216, 0x110, v216
	v_lshrrev_b32_e32 v217, 4, v222
	v_lshl_add_u32 v216, v217, 3, v216
	v_add_u32_e32 v216, 0x11400, v216
	s_branch .LBB0_288
; __device__ __forceinline__ unsigned cvt_pk_bf16(float lo, float hi) { const f2_t v = {lo, hi}; const bf2_t b = __builtin_convertvector(v, bf2_t); return __builtin_bit_cast(unsigned, b); }
; __device__ __forceinline__ f32x4 mfma16(bf16x8 a, bf16x8 b, f32x4 c) { return __builtin_amdgcn_mfma_f32_16x16x32_bf16(a, b, c, 0, 0, 0); }
; __device__ void sg_phase(int wv, const Params& p, int jl, unsigned char* lds) {
;     ...
;         const float* ws = p.a_w_s + ((size_t)jl * 8 + g) * 128 * 128;
; #pragma unroll
;         for (int ps = 0; ps < 8; ++ps) { const int idx = tid + ps * NTHR, t = idx >> 5, s4 = (idx & 31) * 4;
;             const f32x4 wv = *(const f32x4*)(ws + t * 128 + s4); const f32x4 r4 = *(const f32x4*)(rsL + s4); const f32x4 x = wv * r4;
;             u32x2 pk; pk.x = cvt_pk_bf16(x[0], x[1]); pk.y = cvt_pk_bf16(x[2], x[3]); *(u32x2*)(WsL + t * PW + s4) = pk; }
; #pragma unroll
;         for (int ps = 0; ps < 4; ++ps) { const int idx = tid + ps * NTHR, s = idx & 127, d8 = (idx >> 7) * 8;
;             const bf16x8 v = *(const bf16x8*)(uv + (size_t)(t0 + s) * 2048 + 1024 + g * 128 + d8);
; #pragma unroll
;             for (int e = 0; e < 8; ++e) VTL[(d8 + e) * PW + s] = (bf16_t)v[e]; }
;         __syncthreads();
;         bf16x8 af[4];
; #pragma unroll
;         for (int kk = 0; kk < 4; ++kk) af[kk] = *(const bf16x8*)(WsL + (16 * w + lr) * PW + 32 * kk + 8 * lq);
;         const int tok = t0 + 16 * w + lr; const float bs = p.a_b_s[((size_t)jl * 8 + g) * 128 + 16 * w + lr];
; #pragma unroll
;         for (int db = 0; db < 8; ++db) { f32x4 acc = {0, 0, 0, 0};
; #pragma unroll
;             for (int kk = 0; kk < 4; ++kk) { const bf16x8 bf = *(const bf16x8*)(VTL + (16 * db + lr) * PW + 32 * kk + 8 * lq); acc = mfma16(bf, af[kk], acc); }
;             const int col = g * 128 + 16 * db + 4 * lq; const f32x4 gv = *(const f32x4*)(p.a_g_v + jl * DM + col);
;             bf16_t* up = uv + (size_t)tok * 2048 + col; const u32x2 uu = *(const u32x2*)up;
.LBB0_287:
	s_or_b64 exec, exec, s[16:17]
	s_and_b32 s6, s22, 0x380
	s_or_b32 s7, s20, s6
	s_lshl_b32 s36, s7, 9
	v_lshl_add_u64 v[10:11], v[42:43], 0, s[36:37]
	v_lshl_add_u64 v[84:85], v[18:19], 2, v[10:11]
	global_load_dwordx4 v[100:103], v[84:85], off
	v_lshl_add_u64 v[86:87], v[20:21], 2, v[10:11]
	global_load_dwordx4 v[104:107], v[86:87], off
	v_lshl_add_u64 v[88:89], v[22:23], 2, v[10:11]
	global_load_dwordx4 v[108:111], v[88:89], off
	v_lshl_add_u64 v[90:91], v[24:25], 2, v[10:11]
	global_load_dwordx4 v[112:115], v[90:91], off
	v_lshl_add_u64 v[92:93], v[26:27], 2, v[10:11]
	global_load_dwordx4 v[116:119], v[92:93], off
	v_lshl_add_u64 v[94:95], v[28:29], 2, v[10:11]
	global_load_dwordx4 v[120:123], v[94:95], off
	v_lshl_add_u64 v[96:97], v[30:31], 2, v[10:11]
	global_load_dwordx4 v[124:127], v[96:97], off
	v_lshl_add_u64 v[98:99], v[32:33], 2, v[10:11]
	global_load_dwordx4 v[128:131], v[98:99], off
	s_lshl_b32 s36, s6, 1
	v_add_u32_e32 v48, s42, v52
	v_ashrrev_i32_e32 v49, 31, v48
	v_or_b32_e32 v82, s6, v53
	v_lshlrev_b64 v[48:49], 12, v[48:49]
	v_lshl_add_u64 v[48:49], s[76:77], 0, v[48:49]
	v_mov_b32_e32 v83, v0
	v_or_b32_e32 v2, s42, v51
	v_ashrrev_i32_e32 v3, 31, v2
	v_lshlrev_b64 v[2:3], 12, v[2:3]
	v_lshl_add_u64 v[2:3], s[76:77], 0, v[2:3]
	v_lshl_add_u64 v[6:7], v[2:3], 0, s[36:37]
	s_lshl_b32 s16, s42, 12
	s_add_u32 s16, s16, s36
	s_mov_b32 s17, 0
	v_lshl_add_u64 v[132:133], v[214:215], 0, s[16:17]
	v_mov_b32_e32 v248, v132
	v_mov_b32_e32 v249, v133
	s_mov_b64 s[16:17], 0x20000
	global_load_dwordx4 v[140:143], v[132:133], off offset:2048
	global_load_dwordx4 v[232:235], v[132:133], off
	v_lshl_add_u64 v[132:133], v[132:133], 0, s[16:17]
	global_load_dwordx4 v[144:147], v[132:133], off offset:2048
	global_load_dwordx4 v[236:239], v[132:133], off
	v_lshl_add_u64 v[132:133], v[132:133], 0, s[16:17]
	global_load_dwordx4 v[148:151], v[132:133], off offset:2048
	global_load_dwordx4 v[240:243], v[132:133], off
	v_lshl_add_u64 v[132:133], v[132:133], 0, s[16:17]
	global_load_dwordx4 v[152:155], v[132:133], off offset:2048
	global_load_dwordx4 v[244:247], v[132:133], off
	s_lshl_b32 s36, s7, 2
	v_lshl_add_u64 v[72:73], v[44:45], 0, s[36:37]
	global_load_dword v46, v[72:73], off
	v_lshlrev_b32_e32 v72, 2, v82
	v_lshlrev_b32_e32 v82, 1, v82
	v_lshl_add_u64 v[48:49], v[48:49], 0, v[82:83]
	global_load_dwordx4 v[180:183], v72, s[14:15]
	global_load_dwordx4 v[184:187], v72, s[14:15] offset:64
	global_load_dwordx4 v[188:191], v72, s[14:15] offset:128
	global_load_dwordx4 v[192:195], v72, s[14:15] offset:192
	global_load_dwordx4 v[196:199], v72, s[14:15] offset:256
	global_load_dwordx4 v[200:203], v72, s[14:15] offset:320
	global_load_dwordx4 v[204:207], v72, s[14:15] offset:384
	global_load_dwordx4 v[208:211], v72, s[14:15] offset:448
	v_readlane_b32 s6, v254, 42
	s_add_i32 s23, s23, s34
	s_add_i32 s22, s22, s92
	s_add_i32 s21, s21, s6
	s_cmpk_lt_i32 s23, 0x800
	s_waitcnt lgkmcnt(0)
	s_barrier
	ds_read_b128 v[6:9], v50
	s_waitcnt vmcnt(17) lgkmcnt(0)
	v_pk_mul_f32 v[102:103], v[102:103], v[8:9]
	v_pk_mul_f32 v[100:101], v[100:101], v[6:7]
	v_pk_mul_f32 v[106:107], v[106:107], v[8:9]
	v_pk_mul_f32 v[104:105], v[104:105], v[6:7]
	v_pk_mul_f32 v[110:111], v[110:111], v[8:9]
	v_pk_mul_f32 v[108:109], v[108:109], v[6:7]
	v_pk_mul_f32 v[114:115], v[114:115], v[8:9]
	v_pk_mul_f32 v[112:113], v[112:113], v[6:7]
	v_pk_mul_f32 v[118:119], v[118:119], v[8:9]
	v_pk_mul_f32 v[116:117], v[116:117], v[6:7]
	v_pk_mul_f32 v[122:123], v[122:123], v[8:9]
	v_pk_mul_f32 v[120:121], v[120:121], v[6:7]
	v_pk_mul_f32 v[126:127], v[126:127], v[8:9]
	v_pk_mul_f32 v[124:125], v[124:125], v[6:7]
	v_pk_mul_f32 v[130:131], v[130:131], v[8:9]
	v_pk_mul_f32 v[128:129], v[128:129], v[6:7]
	v_cvt_pk_bf16_f32 v100, v100, v101
	v_cvt_pk_bf16_f32 v101, v102, v103
	v_cvt_pk_bf16_f32 v104, v104, v105
	v_cvt_pk_bf16_f32 v105, v106, v107
	v_cvt_pk_bf16_f32 v108, v108, v109
	v_cvt_pk_bf16_f32 v109, v110, v111
	v_cvt_pk_bf16_f32 v112, v112, v113
	v_cvt_pk_bf16_f32 v113, v114, v115
	v_cvt_pk_bf16_f32 v116, v116, v117
	v_cvt_pk_bf16_f32 v117, v118, v119
	v_cvt_pk_bf16_f32 v120, v120, v121
	v_cvt_pk_bf16_f32 v121, v122, v123
	v_cvt_pk_bf16_f32 v124, v124, v125
	v_cvt_pk_bf16_f32 v125, v126, v127
	v_cvt_pk_bf16_f32 v128, v128, v129
	v_cvt_pk_bf16_f32 v129, v130, v131
	ds_write_b64 v54, v[100:101]
	ds_write_b64 v55, v[104:105]
	ds_write_b64 v56, v[108:109]
	ds_write_b64 v57, v[112:113]
	ds_write_b64 v58, v[116:117]
	ds_write_b64 v59, v[120:121]
	ds_write_b64 v60, v[124:125]
	ds_write_b64 v61, v[128:129]
	s_waitcnt vmcnt(9)
	ds_write_b128 v212, v[140:143]
	ds_write_b128 v212, v[144:147] offset:8192
	ds_write_b128 v212, v[148:151] offset:16384
	ds_write_b128 v212, v[152:155] offset:24576
	ds_write_b128 v213, v[232:235]
	ds_write_b128 v213, v[236:239] offset:8704
	ds_write_b128 v213, v[240:243] offset:17408
	ds_write_b128 v213, v[244:247] offset:26112
	s_waitcnt lgkmcnt(0)
	s_barrier
; __device__ __forceinline__ unsigned cvt_pk_bf16(float lo, float hi) { const f2_t v = {lo, hi}; const bf2_t b = __builtin_convertvector(v, bf2_t); return __builtin_bit_cast(unsigned, b); }
; __device__ __forceinline__ f32x4 mfma16(bf16x8 a, bf16x8 b, f32x4 c) { return __builtin_amdgcn_mfma_f32_16x16x32_bf16(a, b, c, 0, 0, 0); }
; __device__ void sg_phase(int wv, const Params& p, int jl, unsigned char* lds) {
;     ...
; #pragma unroll
;         for (int db = 0; db < 8; ++db) { f32x4 acc = {0, 0, 0, 0};
; #pragma unroll
;             for (int kk = 0; kk < 4; ++kk) { const bf16x8 bf = *(const bf16x8*)(VTL + (16 * db + lr) * PW + 32 * kk + 8 * lq); acc = mfma16(bf, af[kk], acc); }
;             const int col = g * 128 + 16 * db + 4 * lq; const f32x4 gv = *(const f32x4*)(p.a_g_v + jl * DM + col);
;             bf16_t* up = uv + (size_t)tok * 2048 + col; const u32x2 uu = *(const u32x2*)up;
;             const float u0 = __uint_as_float(uu.x << 16), u1 = __uint_as_float(uu.x & 0xffff0000u), u2 = __uint_as_float(uu.y << 16), u3 = __uint_as_float(uu.y & 0xffff0000u);
;             const f32x4 sv = acc * gv + bs; u32x2 o; o.x = cvt_pk_bf16(u0 * sv[0], u1 * sv[1]); o.y = cvt_pk_bf16(u2 * sv[2], u3 * sv[3]);
;             *(u32x2*)up = o; }
	ds_read_b128 v[14:17], v70
	ds_read_b128 v[10:13], v70 offset:64
	ds_read_b128 v[6:9], v70 offset:128
	ds_read_b128 v[2:5], v70 offset:192
	v_mov_b32_e32 v220, v218
	v_mov_b32_e32 v221, v219
	ds_read_b64_tr_b16 v[72:73], v220
	ds_read_b64_tr_b16 v[74:75], v221
	ds_read_b64_tr_b16 v[76:77], v220 offset:8192
	ds_read_b64_tr_b16 v[78:79], v221 offset:8192
	s_waitcnt lgkmcnt(2)
	ds_read_b64 v[156:157], v216
	ds_read_b64 v[158:159], v216 offset:32
	ds_read_b64 v[160:161], v216 offset:64
	ds_read_b64 v[162:163], v216 offset:96
	ds_read_b64 v[164:165], v216 offset:128
	ds_read_b64 v[166:167], v216 offset:160
	ds_read_b64 v[168:169], v216 offset:192
	ds_read_b64 v[170:171], v216 offset:224
	v_mfma_f32_16x16x32_bf16 v[72:75], v[72:75], v[14:17], 0
	s_waitcnt lgkmcnt(0)
	v_mfma_f32_16x16x32_bf16 v[72:75], v[76:79], v[10:13], v[72:75]
	ds_read_b64_tr_b16 v[76:77], v220 offset:16384
	ds_read_b64_tr_b16 v[78:79], v221 offset:16384
	s_waitcnt lgkmcnt(0)
	v_mfma_f32_16x16x32_bf16 v[72:75], v[76:79], v[6:9], v[72:75]
	ds_read_b64_tr_b16 v[76:77], v220 offset:24576
	ds_read_b64_tr_b16 v[78:79], v221 offset:24576
	s_waitcnt lgkmcnt(0)
	v_mfma_f32_16x16x32_bf16 v[74:77], v[76:79], v[2:5], v[72:75]
	s_nop 4
	s_waitcnt vmcnt(7)
	s_nop 7
	v_pk_fma_f32 v[74:75], v[74:75], v[180:181], v[46:47] op_sel_hi:[1,1,0]
	v_lshlrev_b32_e32 v78, 16, v156
	v_and_b32_e32 v79, 0xffff0000, v156
	v_pk_fma_f32 v[76:77], v[76:77], v[182:183], v[46:47] op_sel_hi:[1,1,0]
	v_pk_mul_f32 v[74:75], v[74:75], v[78:79]
	v_lshlrev_b32_e32 v78, 16, v157
	v_and_b32_e32 v79, 0xffff0000, v157
	v_pk_mul_f32 v[76:77], v[76:77], v[78:79]
	v_cvt_pk_bf16_f32 v74, v74, v75
	v_cvt_pk_bf16_f32 v75, v76, v77
	ds_write_b64 v216, v[74:75]
	v_xor_b32_e32 v220, 0x20, v218
	v_xor_b32_e32 v221, 0x20, v219
	ds_read_b64_tr_b16 v[74:75], v220
	ds_read_b64_tr_b16 v[76:77], v221
	ds_read_b64_tr_b16 v[78:79], v220 offset:8192
	ds_read_b64_tr_b16 v[80:81], v221 offset:8192
	s_waitcnt lgkmcnt(2)
	v_mfma_f32_16x16x32_bf16 v[74:77], v[74:77], v[14:17], 0
	s_waitcnt lgkmcnt(0)
	v_mfma_f32_16x16x32_bf16 v[74:77], v[78:81], v[10:13], v[74:77]
	ds_read_b64_tr_b16 v[78:79], v220 offset:16384
	ds_read_b64_tr_b16 v[80:81], v221 offset:16384
	s_waitcnt lgkmcnt(0)
	v_mfma_f32_16x16x32_bf16 v[74:77], v[78:81], v[6:9], v[74:77]
	ds_read_b64_tr_b16 v[78:79], v220 offset:24576
	ds_read_b64_tr_b16 v[80:81], v221 offset:24576
	s_waitcnt lgkmcnt(0)
	v_mfma_f32_16x16x32_bf16 v[74:77], v[78:81], v[2:5], v[74:77]
	s_waitcnt vmcnt(6)
	s_nop 7
	s_nop 4
	v_pk_fma_f32 v[74:75], v[74:75], v[184:185], v[46:47] op_sel_hi:[1,1,0]
	v_lshlrev_b32_e32 v78, 16, v158
	v_and_b32_e32 v79, 0xffff0000, v158
	v_pk_fma_f32 v[76:77], v[76:77], v[186:187], v[46:47] op_sel_hi:[1,1,0]
	v_pk_mul_f32 v[74:75], v[74:75], v[78:79]
	v_lshlrev_b32_e32 v78, 16, v159
	v_and_b32_e32 v79, 0xffff0000, v159
	v_pk_mul_f32 v[76:77], v[76:77], v[78:79]
	v_cvt_pk_bf16_f32 v74, v74, v75
	v_cvt_pk_bf16_f32 v75, v76, v77
	ds_write_b64 v216, v[74:75] offset:32
	v_xor_b32_e32 v220, 0x40, v218
	v_xor_b32_e32 v221, 0x40, v219
	ds_read_b64_tr_b16 v[74:75], v220
	ds_read_b64_tr_b16 v[76:77], v221
	ds_read_b64_tr_b16 v[78:79], v220 offset:8192
	ds_read_b64_tr_b16 v[80:81], v221 offset:8192
	s_waitcnt lgkmcnt(2)
	v_mfma_f32_16x16x32_bf16 v[74:77], v[74:77], v[14:17], 0
	s_waitcnt lgkmcnt(0)
	v_mfma_f32_16x16x32_bf16 v[74:77], v[78:81], v[10:13], v[74:77]
	ds_read_b64_tr_b16 v[78:79], v220 offset:16384
	ds_read_b64_tr_b16 v[80:81], v221 offset:16384
	s_waitcnt lgkmcnt(0)
	v_mfma_f32_16x16x32_bf16 v[74:77], v[78:81], v[6:9], v[74:77]
	ds_read_b64_tr_b16 v[78:79], v220 offset:24576
	ds_read_b64_tr_b16 v[80:81], v221 offset:24576
	s_waitcnt lgkmcnt(0)
	v_mfma_f32_16x16x32_bf16 v[74:77], v[78:81], v[2:5], v[74:77]
	s_waitcnt vmcnt(5)
	s_nop 7
	s_nop 4
	v_pk_fma_f32 v[74:75], v[74:75], v[188:189], v[46:47] op_sel_hi:[1,1,0]
	v_lshlrev_b32_e32 v78, 16, v160
	v_and_b32_e32 v79, 0xffff0000, v160
	v_pk_fma_f32 v[76:77], v[76:77], v[190:191], v[46:47] op_sel_hi:[1,1,0]
	v_pk_mul_f32 v[74:75], v[74:75], v[78:79]
	v_lshlrev_b32_e32 v78, 16, v161
	v_and_b32_e32 v79, 0xffff0000, v161
	v_pk_mul_f32 v[76:77], v[76:77], v[78:79]
	v_cvt_pk_bf16_f32 v74, v74, v75
	v_cvt_pk_bf16_f32 v75, v76, v77
	ds_write_b64 v216, v[74:75] offset:64
	v_xor_b32_e32 v220, 0x60, v218
	v_xor_b32_e32 v221, 0x60, v219
	ds_read_b64_tr_b16 v[74:75], v220
	ds_read_b64_tr_b16 v[76:77], v221
	ds_read_b64_tr_b16 v[78:79], v220 offset:8192
	ds_read_b64_tr_b16 v[80:81], v221 offset:8192
	s_waitcnt lgkmcnt(2)
	v_mfma_f32_16x16x32_bf16 v[74:77], v[74:77], v[14:17], 0
	s_waitcnt lgkmcnt(0)
	v_mfma_f32_16x16x32_bf16 v[74:77], v[78:81], v[10:13], v[74:77]
	ds_read_b64_tr_b16 v[78:79], v220 offset:16384
	ds_read_b64_tr_b16 v[80:81], v221 offset:16384
	s_waitcnt lgkmcnt(0)
	v_mfma_f32_16x16x32_bf16 v[74:77], v[78:81], v[6:9], v[74:77]
	ds_read_b64_tr_b16 v[78:79], v220 offset:24576
	ds_read_b64_tr_b16 v[80:81], v221 offset:24576
	s_waitcnt lgkmcnt(0)
	v_mfma_f32_16x16x32_bf16 v[74:77], v[78:81], v[2:5], v[74:77]
	s_waitcnt vmcnt(4)
	s_nop 7
	s_nop 4
	v_pk_fma_f32 v[74:75], v[74:75], v[192:193], v[46:47] op_sel_hi:[1,1,0]
	v_lshlrev_b32_e32 v78, 16, v162
	v_and_b32_e32 v79, 0xffff0000, v162
	v_pk_fma_f32 v[76:77], v[76:77], v[194:195], v[46:47] op_sel_hi:[1,1,0]
	v_pk_mul_f32 v[74:75], v[74:75], v[78:79]
	v_lshlrev_b32_e32 v78, 16, v163
	v_and_b32_e32 v79, 0xffff0000, v163
	v_pk_mul_f32 v[76:77], v[76:77], v[78:79]
	v_cvt_pk_bf16_f32 v74, v74, v75
	v_cvt_pk_bf16_f32 v75, v76, v77
	ds_write_b64 v216, v[74:75] offset:96
	v_xor_b32_e32 v220, 0x80, v218
	v_xor_b32_e32 v221, 0x80, v219
	ds_read_b64_tr_b16 v[74:75], v220
	ds_read_b64_tr_b16 v[76:77], v221
	ds_read_b64_tr_b16 v[78:79], v220 offset:8192
	ds_read_b64_tr_b16 v[80:81], v221 offset:8192
	s_waitcnt lgkmcnt(2)
; __device__ __forceinline__ unsigned cvt_pk_bf16(float lo, float hi) { const f2_t v = {lo, hi}; const bf2_t b = __builtin_convertvector(v, bf2_t); return __builtin_bit_cast(unsigned, b); }
; __device__ __forceinline__ f32x4 mfma16(bf16x8 a, bf16x8 b, f32x4 c) { return __builtin_amdgcn_mfma_f32_16x16x32_bf16(a, b, c, 0, 0, 0); }
; __device__ void sg_phase(int wv, const Params& p, int jl, unsigned char* lds) {
;     ...
; #pragma unroll
;         for (int db = 0; db < 8; ++db) { f32x4 acc = {0, 0, 0, 0};
; #pragma unroll
;             for (int kk = 0; kk < 4; ++kk) { const bf16x8 bf = *(const bf16x8*)(VTL + (16 * db + lr) * PW + 32 * kk + 8 * lq); acc = mfma16(bf, af[kk], acc); }
;             const int col = g * 128 + 16 * db + 4 * lq; const f32x4 gv = *(const f32x4*)(p.a_g_v + jl * DM + col);
;             bf16_t* up = uv + (size_t)tok * 2048 + col; const u32x2 uu = *(const u32x2*)up;
;             const float u0 = __uint_as_float(uu.x << 16), u1 = __uint_as_float(uu.x & 0xffff0000u), u2 = __uint_as_float(uu.y << 16), u3 = __uint_as_float(uu.y & 0xffff0000u);
;             const f32x4 sv = acc * gv + bs; u32x2 o; o.x = cvt_pk_bf16(u0 * sv[0], u1 * sv[1]); o.y = cvt_pk_bf16(u2 * sv[2], u3 * sv[3]);
;             *(u32x2*)up = o; }
;         __syncthreads();
;     }
	v_mfma_f32_16x16x32_bf16 v[74:77], v[74:77], v[14:17], 0
	s_waitcnt lgkmcnt(0)
	v_mfma_f32_16x16x32_bf16 v[74:77], v[78:81], v[10:13], v[74:77]
	ds_read_b64_tr_b16 v[78:79], v220 offset:16384
	ds_read_b64_tr_b16 v[80:81], v221 offset:16384
	s_waitcnt lgkmcnt(0)
	v_mfma_f32_16x16x32_bf16 v[74:77], v[78:81], v[6:9], v[74:77]
	ds_read_b64_tr_b16 v[78:79], v220 offset:24576
	ds_read_b64_tr_b16 v[80:81], v221 offset:24576
	s_waitcnt lgkmcnt(0)
	v_mfma_f32_16x16x32_bf16 v[74:77], v[78:81], v[2:5], v[74:77]
	s_waitcnt vmcnt(3)
	s_nop 7
	s_nop 4
	v_pk_fma_f32 v[74:75], v[74:75], v[196:197], v[46:47] op_sel_hi:[1,1,0]
	v_lshlrev_b32_e32 v78, 16, v164
	v_and_b32_e32 v79, 0xffff0000, v164
	v_pk_fma_f32 v[76:77], v[76:77], v[198:199], v[46:47] op_sel_hi:[1,1,0]
	v_pk_mul_f32 v[74:75], v[74:75], v[78:79]
	v_lshlrev_b32_e32 v78, 16, v165
	v_and_b32_e32 v79, 0xffff0000, v165
	v_pk_mul_f32 v[76:77], v[76:77], v[78:79]
	v_cvt_pk_bf16_f32 v74, v74, v75
	v_cvt_pk_bf16_f32 v75, v76, v77
	ds_write_b64 v216, v[74:75] offset:128
	v_xor_b32_e32 v220, 0xa0, v218
	v_xor_b32_e32 v221, 0xa0, v219
	ds_read_b64_tr_b16 v[74:75], v220
	ds_read_b64_tr_b16 v[76:77], v221
	ds_read_b64_tr_b16 v[78:79], v220 offset:8192
	ds_read_b64_tr_b16 v[80:81], v221 offset:8192
	s_waitcnt lgkmcnt(2)
	v_mfma_f32_16x16x32_bf16 v[74:77], v[74:77], v[14:17], 0
	s_waitcnt lgkmcnt(0)
	v_mfma_f32_16x16x32_bf16 v[74:77], v[78:81], v[10:13], v[74:77]
	ds_read_b64_tr_b16 v[78:79], v220 offset:16384
	ds_read_b64_tr_b16 v[80:81], v221 offset:16384
	s_waitcnt lgkmcnt(0)
	v_mfma_f32_16x16x32_bf16 v[74:77], v[78:81], v[6:9], v[74:77]
	ds_read_b64_tr_b16 v[78:79], v220 offset:24576
	ds_read_b64_tr_b16 v[80:81], v221 offset:24576
	s_waitcnt lgkmcnt(0)
	v_mfma_f32_16x16x32_bf16 v[74:77], v[78:81], v[2:5], v[74:77]
	s_waitcnt vmcnt(2)
	s_nop 7
	s_nop 4
	v_pk_fma_f32 v[74:75], v[74:75], v[200:201], v[46:47] op_sel_hi:[1,1,0]
	v_lshlrev_b32_e32 v78, 16, v166
	v_and_b32_e32 v79, 0xffff0000, v166
	v_pk_fma_f32 v[76:77], v[76:77], v[202:203], v[46:47] op_sel_hi:[1,1,0]
	v_pk_mul_f32 v[74:75], v[74:75], v[78:79]
	v_lshlrev_b32_e32 v78, 16, v167
	v_and_b32_e32 v79, 0xffff0000, v167
	v_pk_mul_f32 v[76:77], v[76:77], v[78:79]
	v_cvt_pk_bf16_f32 v74, v74, v75
	v_cvt_pk_bf16_f32 v75, v76, v77
	ds_write_b64 v216, v[74:75] offset:160
	v_xor_b32_e32 v220, 0xc0, v218
	v_xor_b32_e32 v221, 0xc0, v219
	ds_read_b64_tr_b16 v[74:75], v220
	ds_read_b64_tr_b16 v[76:77], v221
	ds_read_b64_tr_b16 v[78:79], v220 offset:8192
	ds_read_b64_tr_b16 v[80:81], v221 offset:8192
	s_waitcnt lgkmcnt(2)
	v_mfma_f32_16x16x32_bf16 v[74:77], v[74:77], v[14:17], 0
	s_waitcnt lgkmcnt(0)
	v_mfma_f32_16x16x32_bf16 v[74:77], v[78:81], v[10:13], v[74:77]
	ds_read_b64_tr_b16 v[78:79], v220 offset:16384
	ds_read_b64_tr_b16 v[80:81], v221 offset:16384
	s_waitcnt lgkmcnt(0)
	v_mfma_f32_16x16x32_bf16 v[74:77], v[78:81], v[6:9], v[74:77]
	ds_read_b64_tr_b16 v[78:79], v220 offset:24576
	ds_read_b64_tr_b16 v[80:81], v221 offset:24576
	s_waitcnt lgkmcnt(0)
	v_mfma_f32_16x16x32_bf16 v[74:77], v[78:81], v[2:5], v[74:77]
	s_waitcnt vmcnt(1)
	s_nop 7
	s_nop 4
	v_pk_fma_f32 v[74:75], v[74:75], v[204:205], v[46:47] op_sel_hi:[1,1,0]
	v_lshlrev_b32_e32 v78, 16, v168
	v_and_b32_e32 v79, 0xffff0000, v168
	v_pk_fma_f32 v[76:77], v[76:77], v[206:207], v[46:47] op_sel_hi:[1,1,0]
	v_pk_mul_f32 v[74:75], v[74:75], v[78:79]
	v_lshlrev_b32_e32 v78, 16, v169
	v_and_b32_e32 v79, 0xffff0000, v169
	v_pk_mul_f32 v[76:77], v[76:77], v[78:79]
	v_cvt_pk_bf16_f32 v74, v74, v75
	v_cvt_pk_bf16_f32 v75, v76, v77
	ds_write_b64 v216, v[74:75] offset:192
	v_xor_b32_e32 v220, 0xe0, v218
	v_xor_b32_e32 v221, 0xe0, v219
	ds_read_b64_tr_b16 v[74:75], v220
	ds_read_b64_tr_b16 v[76:77], v221
	s_waitcnt lgkmcnt(0)
	v_mfma_f32_16x16x32_bf16 v[14:17], v[74:77], v[14:17], 0
	ds_read_b64_tr_b16 v[74:75], v220 offset:8192
	ds_read_b64_tr_b16 v[76:77], v221 offset:8192
	s_waitcnt lgkmcnt(0)
	v_mfma_f32_16x16x32_bf16 v[10:13], v[74:77], v[10:13], v[14:17]
	s_nop 4
	ds_read_b64_tr_b16 v[14:15], v220 offset:16384
	ds_read_b64_tr_b16 v[16:17], v221 offset:16384
	s_waitcnt lgkmcnt(0)
	v_mfma_f32_16x16x32_bf16 v[6:9], v[14:17], v[6:9], v[10:13]
	s_nop 2
	ds_read_b64_tr_b16 v[10:11], v220 offset:24576
	ds_read_b64_tr_b16 v[12:13], v221 offset:24576
	s_waitcnt lgkmcnt(0)
	v_mfma_f32_16x16x32_bf16 v[2:5], v[10:13], v[2:5], v[6:9]
	s_nop 2
	s_waitcnt vmcnt(0)
	s_nop 7
	s_nop 1
	v_pk_fma_f32 v[2:3], v[2:3], v[208:209], v[46:47] op_sel_hi:[1,1,0]
	v_lshlrev_b32_e32 v6, 16, v170
	v_and_b32_e32 v7, 0xffff0000, v170
	v_pk_fma_f32 v[4:5], v[4:5], v[210:211], v[46:47] op_sel_hi:[1,1,0]
	v_pk_mul_f32 v[2:3], v[2:3], v[6:7]
	v_lshlrev_b32_e32 v6, 16, v171
	v_and_b32_e32 v7, 0xffff0000, v171
	v_pk_mul_f32 v[4:5], v[4:5], v[6:7]
	v_cvt_pk_bf16_f32 v2, v2, v3
	v_cvt_pk_bf16_f32 v3, v4, v5
	ds_write_b64 v216, v[2:3] offset:224
	s_waitcnt lgkmcnt(0)
	s_barrier
	ds_read_b128 v[232:235], v213
	ds_read_b128 v[236:239], v213 offset:8704
	ds_read_b128 v[240:243], v213 offset:17408
	ds_read_b128 v[244:247], v213 offset:26112
	s_mov_b64 s[16:17], 0x20000
	v_mov_b32_e32 v132, v248
	v_mov_b32_e32 v133, v249
	s_waitcnt lgkmcnt(3)
	global_store_dwordx4 v[132:133], v[232:235], off
	v_lshl_add_u64 v[132:133], v[132:133], 0, s[16:17]
	s_waitcnt lgkmcnt(2)
	global_store_dwordx4 v[132:133], v[236:239], off
	v_lshl_add_u64 v[132:133], v[132:133], 0, s[16:17]
	s_waitcnt lgkmcnt(1)
	global_store_dwordx4 v[132:133], v[240:243], off
	v_lshl_add_u64 v[132:133], v[132:133], 0, s[16:17]
	s_waitcnt lgkmcnt(0)
	global_store_dwordx4 v[132:133], v[244:247], off
	s_barrier
	s_cbranch_scc0 .LBB0_290

; __device__ __forceinline__ int otid(int wv) { int t; asm volatile("v_mbcnt_lo_u32_b32 %0, -1, 0\n\tv_mbcnt_hi_u32_b32 %0, -1, %0\n\tv_lshl_add_u32 %0, %1, 6, %0" : "=&v"(t) : "s"(wv)); return t; }
; template <int N1> __device__ void fft1_units(int wv, const Params& p, unsigned char* lds, int seq_lo, int nseq, int part, int nparts) {
;     const int tid = otid(wv), lane = tid & 63, w = __builtin_amdgcn_readfirstlane(tid >> 6), lr = lane & 15, lq = lane >> 4;
;     constexpr int PW = N1 + 8, NB = N1 / 16, NK = N1 / 32; constexpr int S = N1 * 128;
;     const bf16_t* z = (const bf16_t*)(p.ws + WS_BIG1); bf16_t* A1 = (bf16_t*)(p.ws + WS_BIG2);
;     const bf16_t* ctg = (const bf16_t*)(p.ws + WS_TAB + (N1 == 64 ? TAB_CT64 : TAB_CT128)); const bf16_t* stg = (const bf16_t*)(p.ws + WS_TAB + (N1 == 64 ? TAB_ST64 : TAB_ST128));
;     bf16_t* CT = (bf16_t*)lds; bf16_t* ST = CT + N1 * PW; bf16_t* XT = ST + N1 * PW;
;     for (int idx = tid; idx < N1 * N1 / 8; idx += NTHR) { const int r = idx / (N1 / 8), c8 = (idx % (N1 / 8)) * 8;
;         *(bf16x8*)(CT + r * PW + c8) = *(const bf16x8*)(ctg + r * N1 + c8); *(bf16x8*)(ST + r * PW + c8) = *(const bf16x8*)(stg + r * N1 + c8); }
;     __syncthreads();
;     const int nunits = nseq * 128 * 8;
;     for (int unit = part; unit < nunits; unit += nparts) {
;         const int sq = unit / 1024, b = (unit >> 3) & 127, cb = unit & 7;
;         const int seq = seq_lo + sq; const size_t sbase = (size_t)seq * 8192;
;         for (int idx = tid; idx < N1 * 16; idx += NTHR) { const int a = idx % N1, c8 = (idx / N1) * 8;
;             const bf16x8 v = *(const bf16x8*)(z + (sbase + 128 * a + b) * DM + cb * 128 + c8);
; #pragma unroll
;             for (int e = 0; e < 8; ++e) XT[(c8 + e) * PW + a] = (bf16_t)v[e]; }
;         __syncthreads();
;         bf16x8 xf[NK];
; #pragma unroll
;         for (int kk = 0; kk < NK; ++kk) xf[kk] = *(const bf16x8*)(XT + (16 * w + lr) * PW + 32 * kk + 8 * lq);
; #pragma unroll
;         for (int i = 0; i < NB; ++i) { f32x4 ar = {0, 0, 0, 0}, as = {0, 0, 0, 0};
; #pragma unroll
;             for (int kk = 0; kk < NK; ++kk) { const bf16x8 cf = *(const bf16x8*)(CT + (16 * i + lr) * PW + 32 * kk + 8 * lq), sf = *(const bf16x8*)(ST + (16 * i + lr) * PW + 32 * kk + 8 * lq);
;                 ar = mfma16(xf[kk], cf, ar); as = mfma16(xf[kk], sf, as); }
.LBB0_313:
	s_or_b64 exec, exec, s[6:7]
	v_readlane_b32 s6, v254, 16
	v_readlane_b32 s7, v254, 17
	s_andn2_b64 vcc, exec, s[6:7]
	s_waitcnt lgkmcnt(0)
	s_barrier
	s_cbranch_vccnz .LBB0_319
	s_ashr_i32 s7, s14, 2
	s_and_b32 s6, s7, -16
	v_bfi_b32 v3, -16, s7, v1
	s_movk_i32 s7, 0x110
	v_mul_lo_u32 v3, v3, s7
	s_ashr_i32 s7, s6, 31
	s_lshl_b64 s[6:7], s[6:7], 1
	v_readlane_b32 s10, v254, 13
	v_bfe_u32 v2, v1, 4, 2
	v_readlane_b32 s14, v254, 57
	v_readlane_b32 s11, v254, 14
	s_add_u32 s6, s10, s6
	v_and_b32_e32 v4, 15, v1
	v_add_u32_e32 v5, s14, v3
	v_lshlrev_b32_e32 v6, 4, v2
	v_lshlrev_b32_e32 v2, 3, v2
	s_addc_u32 s7, s11, s7
	v_mov_b32_e32 v3, v0
	v_lshl_add_u64 v[18:19], s[6:7], 0, v[2:3]
	v_or_b32_e32 v3, 32, v4
	v_add_u32_e32 v7, 0, v6
	v_or_b32_e32 v8, 48, v4
	v_mul_u32_u24_e32 v9, 0x88, v3
	v_lshl_add_u32 v23, v9, 1, v7
	v_mul_u32_u24_e32 v9, 0x88, v8
	v_lshl_add_u32 v25, v9, 1, v7
	v_or_b32_e32 v9, 64, v4
	v_or_b32_e32 v10, 0x50, v4
	v_mul_u32_u24_e32 v11, 0x88, v9
	v_lshl_add_u32 v27, v11, 1, v7
	v_mul_u32_u24_e32 v11, 0x88, v10
	v_lshl_add_u32 v38, v11, 1, v7
	v_or_b32_e32 v11, 0x60, v4
	v_mul_u32_u24_e32 v2, 0x88, v4
	v_or_b32_e32 v12, 0x70, v4
	v_mul_u32_u24_e32 v13, 0x88, v11
	v_lshl_add_u32 v21, v2, 1, v7
	v_or_b32_e32 v2, 16, v4
	v_lshl_add_u32 v39, v13, 1, v7
	v_mul_u32_u24_e32 v13, 0x88, v12
	v_lshlrev_b32_e32 v20, 7, v4
	v_lshlrev_b32_e32 v22, 7, v2
	v_lshlrev_b32_e32 v24, 7, v3
	v_lshlrev_b32_e32 v26, 7, v8
	v_lshlrev_b32_e32 v28, 7, v9
	v_mov_b32_e32 v29, v0
	v_lshlrev_b32_e32 v30, 7, v10
	v_mov_b32_e32 v31, v0
	v_lshlrev_b32_e32 v32, 7, v11
	v_mov_b32_e32 v33, v0
	v_lshl_add_u32 v40, v13, 1, v7
	v_lshlrev_b32_e32 v34, 7, v12
	v_mov_b32_e32 v35, v0
	v_lshlrev_b32_e32 v41, 1, v2
	v_lshlrev_b32_e32 v42, 1, v4
	v_lshlrev_b32_e32 v43, 1, v8
	v_lshlrev_b32_e32 v44, 1, v3
	v_lshlrev_b32_e32 v45, 1, v10
	v_lshlrev_b32_e32 v46, 1, v9
	v_lshlrev_b32_e32 v47, 1, v12
	v_lshlrev_b32_e32 v48, 1, v11
	v_lshlrev_b32_e32 v49, 7, v1
	v_lshl_add_u32 v50, v1, 1, s14
	v_add_u32_e32 v51, v5, v6
	v_readlane_b32 s20, v254, 15
	v_mbcnt_lo_u32_b32 v224, -1, 0
	v_mbcnt_hi_u32_b32 v224, -1, v224
	v_lshl_add_u32 v225, s33, 6, v224
	v_lshrrev_b32_e32 v226, 4, v225
	v_and_b32_e32 v227, 15, v225
	v_and_b32_e32 v228, 3, v226
	v_lshlrev_b32_e32 v228, 2, v228
	v_bfe_u32 v229, v226, 2, 2
	v_or_b32_e32 v228, v228, v229
	v_xor_b32_e32 v228, v227, v228
	v_lshlrev_b32_e32 v228, 4, v228
	v_lshl_add_u32 v202, v226, 8, v228
	v_add_u32_e32 v202, 0x11000, v202
	v_lshlrev_b32_e32 v200, 18, v226
	v_lshl_add_u32 v200, v227, 4, v200
	v_mov_b32_e32 v201, 0
	v_bfe_u32 v226, v224, 2, 2
	v_and_b32_e32 v227, 3, v224
	v_lshrrev_b32_e32 v228, 4, v224
	v_lshl_add_u32 v229, v228, 3, v226
	v_lshlrev_b32_e32 v230, 2, v226
	v_lshlrev_b32_e32 v228, 1, v228
	v_and_b32_e32 v231, 3, v228
	v_or_b32_e32 v231, v230, v231
	v_add_u32_e32 v228, 1, v228
	v_and_b32_e32 v228, 3, v228
	v_or_b32_e32 v228, v230, v228
	s_lshl_b32 s14, s33, 1
	v_lshrrev_b32_e32 v230, 1, v227
	v_add_u32_e32 v230, s14, v230
	v_and_b32_e32 v227, 1, v227
	v_lshlrev_b32_e32 v227, 3, v227
	v_xor_b32_e32 v231, v230, v231
	v_lshl_add_u32 v231, v231, 4, v227
	v_lshl_add_u32 v222, v229, 8, v231
	v_add_u32_e32 v222, 0x11000, v222
	v_xor_b32_e32 v228, v230, v228
	v_lshl_add_u32 v228, v228, 4, v227
	v_add_u32_e32 v229, 4, v229
	v_lshl_add_u32 v223, v229, 8, v228
	v_add_u32_e32 v223, 0x11000, v223
	v_and_b32_e32 v232, 15, v224
	v_mul_u32_u24_e32 v232, 0x110, v232
	v_lshrrev_b32_e32 v233, 4, v224
	v_lshl_add_u32 v232, v233, 3, v232
	s_lshl_b32 s14, s33, 5
	v_add_u32_e32 v232, s14, v232
	v_add_u32_e32 v232, 0x11000, v232
	v_lshrrev_b32_e32 v234, 4, v225
	v_and_b32_e32 v244, 15, v225
	v_lshlrev_b32_e32 v244, 4, v244
	v_mul_u32_u24_e32 v233, 0x110, v234
	v_add_u32_e32 v233, v233, v244
	v_add_u32_e32 v233, 0x11000, v233
	v_lshl_add_u32 v244, v234, 19, v244
	v_mov_b32_e32 v245, 0
	v_readlane_b32 s14, v254, 13
	v_readlane_b32 s15, v254, 14
	s_nop 0
	v_lshl_add_u64 v[244:245], s[14:15], 0, v[244:245]
	s_branch .LBB0_316
.LBB0_315:
	s_or_b64 exec, exec, s[10:11]
	s_waitcnt lgkmcnt(0)
	s_barrier
	ds_read_b64_tr_b16 v[14:15], v222
	ds_read_b64_tr_b16 v[16:17], v223
	ds_read_b64_tr_b16 v[10:11], v222 offset:8192
	ds_read_b64_tr_b16 v[12:13], v223 offset:8192
	ds_read_b64_tr_b16 v[6:7], v222 offset:16384
	ds_read_b64_tr_b16 v[8:9], v223 offset:16384
	ds_read_b64_tr_b16 v[2:3], v222 offset:24576
	ds_read_b64_tr_b16 v[4:5], v223 offset:24576
	ds_read_b128 v[52:55], v21
	ds_read_b128 v[56:59], v21 offset:34816
	ds_read_b128 v[60:63], v21 offset:64
	ds_read_b128 v[64:67], v21 offset:34880
	s_waitcnt lgkmcnt(0)
	s_barrier
; __device__ __forceinline__ unsigned cvt_pk_bf16(float lo, float hi) { const f2_t v = {lo, hi}; const bf2_t b = __builtin_convertvector(v, bf2_t); return __builtin_bit_cast(unsigned, b); }
; __device__ __forceinline__ f32x4 mfma16(bf16x8 a, bf16x8 b, f32x4 c) { return __builtin_amdgcn_mfma_f32_16x16x32_bf16(a, b, c, 0, 0, 0); }
; template <int N1> __device__ void fft1_units(int wv, const Params& p, unsigned char* lds, int seq_lo, int nseq, int part, int nparts) {
;     ...
;         for (int i = 0; i < NB; ++i) { f32x4 ar = {0, 0, 0, 0}, as = {0, 0, 0, 0};
; #pragma unroll
;             for (int kk = 0; kk < NK; ++kk) { const bf16x8 cf = *(const bf16x8*)(CT + (16 * i + lr) * PW + 32 * kk + 8 * lq), sf = *(const bf16x8*)(ST + (16 * i + lr) * PW + 32 * kk + 8 * lq);
;                 ar = mfma16(xf[kk], cf, ar); as = mfma16(xf[kk], sf, as); }
;             const int ka = 16 * i + lr; float tc, ts; sincospif(2.0f * (float)(b * ka) / (float)S, &ts, &tc);
;             const f32x4 re = ar * tc - as * ts, im = -(as * tc) - ar * ts;
;             bf16_t* op = A1 + (sbase + (size_t)ka * 128 + b) * 2048 + cb * 128 + 16 * w + 4 * lq;
;             u32x2 o; o.x = cvt_pk_bf16(re[0], re[1]); o.y = cvt_pk_bf16(re[2], re[3]); *(u32x2*)op = o;
;             o.x = cvt_pk_bf16(im[0], im[1]); o.y = cvt_pk_bf16(im[2], im[3]); *(u32x2*)(op + 1024) = o; }
	v_mfma_f32_16x16x32_bf16 v[52:55], v[14:17], v[52:55], 0
	s_lshl_b32 s36, s22, 1
	v_lshl_add_u64 v[36:37], v[18:19], 0, s[36:37]
	v_mul_u32_u24_e32 v78, s21, v41
	s_waitcnt lgkmcnt(2)
	v_mfma_f32_16x16x32_bf16 v[56:59], v[14:17], v[56:59], 0
	v_mul_u32_u24_e32 v79, s21, v42
	s_mov_b32 s14, 0x38800000
	s_mov_b32 s10, 0x7f800000
	s_waitcnt lgkmcnt(1)
	v_mfma_f32_16x16x32_bf16 v[52:55], v[10:13], v[60:63], v[52:55]
	v_mov_b32_e32 v82, 0xbf1f24be
	v_mov_b32_e32 v83, 0x3e642e9d
	s_brev_b32 s11, 1
	s_waitcnt lgkmcnt(0)
	v_mfma_f32_16x16x32_bf16 v[56:59], v[10:13], v[64:67], v[56:59]
	ds_read_b128 v[60:63], v21 offset:128
	ds_read_b128 v[64:67], v21 offset:34944
	v_mov_b32_e32 v84, 0x7fc00000
	s_add_i32 s20, s20, s40
	s_waitcnt lgkmcnt(1)
	v_mfma_f32_16x16x32_bf16 v[52:55], v[6:9], v[60:63], v[52:55]
	s_cmpk_gt_i32 s20, 0x3ff
	s_waitcnt lgkmcnt(0)
	v_mfma_f32_16x16x32_bf16 v[56:59], v[6:9], v[64:67], v[56:59]
	ds_read_b128 v[60:63], v21 offset:192
	ds_read_b128 v[64:67], v21 offset:35008
	s_waitcnt lgkmcnt(1)
	v_mfma_f32_16x16x32_bf16 v[52:55], v[2:5], v[60:63], v[52:55]
	v_mov_b32_e32 v61, s7
	v_or_b32_e32 v60, s6, v20
	v_lshlrev_b64 v[60:61], 12, v[60:61]
	s_waitcnt lgkmcnt(0)
	v_mfma_f32_16x16x32_bf16 v[56:59], v[2:5], v[64:67], v[56:59]
	v_lshl_add_u64 v[76:77], v[36:37], 0, v[60:61]
	ds_read_b128 v[60:63], v21 offset:4352
	ds_read_b128 v[64:67], v21 offset:39168
	ds_read_b128 v[68:71], v21 offset:4416
	ds_read_b128 v[72:75], v21 offset:39232
	s_waitcnt lgkmcnt(3)
	v_mfma_f32_16x16x32_bf16 v[60:63], v[14:17], v[60:63], 0
	s_waitcnt lgkmcnt(2)
	v_mfma_f32_16x16x32_bf16 v[64:67], v[14:17], v[64:67], 0
	s_waitcnt lgkmcnt(1)
	v_mfma_f32_16x16x32_bf16 v[60:63], v[10:13], v[68:71], v[60:63]
	s_waitcnt lgkmcnt(0)
	v_mfma_f32_16x16x32_bf16 v[64:67], v[10:13], v[72:75], v[64:67]
	ds_read_b128 v[68:71], v21 offset:4480
	ds_read_b128 v[72:75], v21 offset:39296
	s_waitcnt lgkmcnt(1)
	v_mfma_f32_16x16x32_bf16 v[60:63], v[6:9], v[68:71], v[60:63]
	s_waitcnt lgkmcnt(0)
	v_mfma_f32_16x16x32_bf16 v[64:67], v[6:9], v[72:75], v[64:67]
	ds_read_b128 v[68:71], v21 offset:4544
	ds_read_b128 v[72:75], v21 offset:39360
	s_waitcnt lgkmcnt(1)
	v_mfma_f32_16x16x32_bf16 v[60:63], v[2:5], v[68:71], v[60:63]
	v_cvt_f32_u32_e32 v69, v79
	v_cvt_f32_u32_e32 v68, v78
	v_pk_mul_f32 v[68:69], v[68:69], s[14:15] op_sel_hi:[1,0]
	s_nop 0
	v_pk_mul_f32 v[70:71], v[68:69], 0.5 op_sel_hi:[1,0]
	s_waitcnt lgkmcnt(0)
	v_mfma_f32_16x16x32_bf16 v[64:67], v[2:5], v[72:75], v[64:67]
	v_fract_f32_e32 v72, v71
	v_add_f32_e32 v72, v72, v72
	v_cmp_neq_f32_e32 vcc, s10, v71
	s_nop 1
	v_cndmask_b32_e32 v71, 0, v72, vcc
	v_cmp_lt_f32_e32 vcc, 1.0, v69
	s_nop 1
	v_cndmask_b32_e32 v71, v69, v71, vcc
	v_add_f32_e32 v72, v71, v71
	v_rndne_f32_e32 v72, v72
	v_fmac_f32_e32 v71, -0.5, v72
	v_mul_f32_e32 v73, v71, v71
	v_fmamk_f32 v74, v73, 0x3e75aa41, v82
	v_fmaak_f32 v74, v73, v74, 0x40234736
	v_fmaak_f32 v74, v73, v74, 0xc0a55e0e
	v_mul_f32_e32 v75, v71, v73
	v_mul_f32_e32 v74, v75, v74
	v_cvt_i32_f32_e32 v72, v72
	v_fmac_f32_e32 v74, 0x40490fdb, v71
	v_fmamk_f32 v71, v73, 0x3d4be544, v83
	v_fmaak_f32 v71, v73, v71, 0xbfaad1da
	v_fmaak_f32 v71, v73, v71, 0x4081e0d3
	v_fmaak_f32 v71, v73, v71, 0xc09de9e6
	v_fma_f32 v71, v73, v71, 1.0
	v_lshlrev_b32_e32 v73, 30, v72
	v_and_b32_e32 v72, 1, v72
	v_cmp_eq_u32_e32 vcc, 0, v72
	s_nop 1
	v_cndmask_b32_e32 v72, v71, v74, vcc
	v_bitop3_b32 v75, v72, v73, s11 bitop3:0x78
	v_xor_b32_e32 v72, 0x80000000, v74
	v_cndmask_b32_e32 v71, v72, v71, vcc
	v_cmp_lg_f32_e32 vcc, s10, v69
	v_bitop3_b32 v71, v71, v73, s11 bitop3:0x78
	s_nop 0
	v_cndmask_b32_e32 v74, v84, v75, vcc
	v_cndmask_b32_e32 v72, v84, v71, vcc
	v_pk_mul_f32 v[78:79], v[74:75], v[56:57] op_sel_hi:[0,1]
	v_pk_mul_f32 v[80:81], v[74:75], v[58:59] op_sel_hi:[0,1]
	v_pk_fma_f32 v[80:81], v[72:73], v[54:55], v[80:81] op_sel_hi:[0,1,1] neg_lo:[0,0,1] neg_hi:[0,0,1]
	v_pk_fma_f32 v[78:79], v[72:73], v[52:53], v[78:79] op_sel_hi:[0,1,1] neg_lo:[0,0,1] neg_hi:[0,0,1]
	v_pk_mul_f32 v[52:53], v[74:75], v[52:53] op_sel_hi:[0,1]
	v_pk_mul_f32 v[54:55], v[74:75], v[54:55] op_sel_hi:[0,1]
	v_pk_fma_f32 v[54:55], v[58:59], v[72:73], v[54:55] op_sel_hi:[1,0,1] neg_lo:[0,1,1] neg_hi:[0,1,1]
	v_pk_fma_f32 v[52:53], v[56:57], v[72:73], v[52:53] op_sel_hi:[1,0,1] neg_lo:[0,1,1] neg_hi:[0,1,1]
	v_cmp_neq_f32_e32 vcc, s10, v70
	v_cvt_pk_bf16_f32 v52, v52, v53
	v_cvt_pk_bf16_f32 v53, v54, v55
	ds_write_b64 v232, v[52:53] offset:34816
	v_fract_f32_e32 v52, v70
	v_add_f32_e32 v52, v52, v52
	v_cndmask_b32_e32 v52, 0, v52, vcc
	v_cmp_lt_f32_e32 vcc, 1.0, v68
	v_cvt_pk_bf16_f32 v56, v78, v79
	v_cvt_pk_bf16_f32 v57, v80, v81
	v_cndmask_b32_e32 v52, v68, v52, vcc
	v_add_f32_e32 v53, v52, v52
	v_rndne_f32_e32 v53, v53
	v_fmac_f32_e32 v52, -0.5, v53
	v_mul_f32_e32 v54, v52, v52
	v_fmamk_f32 v55, v54, 0x3e75aa41, v82
	v_fmaak_f32 v55, v54, v55, 0x40234736
	ds_write_b64 v232, v[56:57] offset:0
	v_fmaak_f32 v55, v54, v55, 0xc0a55e0e
	v_mul_f32_e32 v56, v52, v54
	v_mul_f32_e32 v55, v56, v55
	v_cvt_i32_f32_e32 v53, v53
	v_fmac_f32_e32 v55, 0x40490fdb, v52
	v_fmamk_f32 v52, v54, 0x3d4be544, v83
	v_fmaak_f32 v52, v54, v52, 0xbfaad1da
	v_fmaak_f32 v52, v54, v52, 0x4081e0d3
	v_fmaak_f32 v52, v54, v52, 0xc09de9e6
	v_fma_f32 v52, v54, v52, 1.0
	v_lshlrev_b32_e32 v54, 30, v53
	v_and_b32_e32 v53, 1, v53
	v_cmp_eq_u32_e32 vcc, 0, v53
	v_mul_u32_u24_e32 v78, s21, v43
	v_mul_u32_u24_e32 v79, s21, v44
	v_cndmask_b32_e32 v53, v52, v55, vcc
	v_xor_b32_e32 v55, 0x80000000, v55
	v_bitop3_b32 v53, v53, v54, s11 bitop3:0x78
	v_cndmask_b32_e32 v52, v55, v52, vcc
	v_cmp_lg_f32_e32 vcc, s10, v68
	v_bitop3_b32 v52, v52, v54, s11 bitop3:0x78
	s_nop 0
	v_cndmask_b32_e32 v54, v84, v53, vcc
	v_cndmask_b32_e32 v52, v84, v52, vcc
	v_pk_mul_f32 v[56:57], v[54:55], v[64:65] op_sel_hi:[0,1]
	v_pk_mul_f32 v[58:59], v[54:55], v[66:67] op_sel_hi:[0,1]
	v_pk_fma_f32 v[56:57], v[52:53], v[60:61], v[56:57] op_sel_hi:[0,1,1] neg_lo:[0,0,1] neg_hi:[0,0,1]
	v_pk_mul_f32 v[60:61], v[54:55], v[60:61] op_sel_hi:[0,1]
	v_pk_mul_f32 v[54:55], v[54:55], v[62:63] op_sel_hi:[0,1]
	v_pk_fma_f32 v[58:59], v[52:53], v[62:63], v[58:59] op_sel_hi:[0,1,1] neg_lo:[0,0,1] neg_hi:[0,0,1]
	v_pk_fma_f32 v[54:55], v[66:67], v[52:53], v[54:55] op_sel_hi:[1,0,1] neg_lo:[0,1,1] neg_hi:[0,1,1]
	v_pk_fma_f32 v[52:53], v[64:65], v[52:53], v[60:61] op_sel_hi:[1,0,1] neg_lo:[0,1,1] neg_hi:[0,1,1]
	v_mov_b32_e32 v61, s7
	v_or_b32_e32 v60, s6, v22
	v_lshlrev_b64 v[60:61], 12, v[60:61]
	v_lshl_add_u64 v[60:61], v[36:37], 0, v[60:61]
	v_cvt_pk_bf16_f32 v56, v56, v57
	v_cvt_pk_bf16_f32 v57, v58, v59
	v_cvt_pk_bf16_f32 v52, v52, v53
	v_cvt_pk_bf16_f32 v53, v54, v55
	ds_write_b64 v232, v[56:57] offset:4352
	ds_write_b64 v232, v[52:53] offset:39168
	ds_read_b128 v[52:55], v23
	ds_read_b128 v[56:59], v23 offset:34816
	ds_read_b128 v[60:63], v23 offset:64
	ds_read_b128 v[64:67], v23 offset:34880
	s_waitcnt lgkmcnt(3)
; __device__ __forceinline__ unsigned cvt_pk_bf16(float lo, float hi) { const f2_t v = {lo, hi}; const bf2_t b = __builtin_convertvector(v, bf2_t); return __builtin_bit_cast(unsigned, b); }
; __device__ __forceinline__ f32x4 mfma16(bf16x8 a, bf16x8 b, f32x4 c) { return __builtin_amdgcn_mfma_f32_16x16x32_bf16(a, b, c, 0, 0, 0); }
; template <int N1> __device__ void fft1_units(int wv, const Params& p, unsigned char* lds, int seq_lo, int nseq, int part, int nparts) {
;     ...
;         for (int i = 0; i < NB; ++i) { f32x4 ar = {0, 0, 0, 0}, as = {0, 0, 0, 0};
; #pragma unroll
;             for (int kk = 0; kk < NK; ++kk) { const bf16x8 cf = *(const bf16x8*)(CT + (16 * i + lr) * PW + 32 * kk + 8 * lq), sf = *(const bf16x8*)(ST + (16 * i + lr) * PW + 32 * kk + 8 * lq);
;                 ar = mfma16(xf[kk], cf, ar); as = mfma16(xf[kk], sf, as); }
;             const int ka = 16 * i + lr; float tc, ts; sincospif(2.0f * (float)(b * ka) / (float)S, &ts, &tc);
;             const f32x4 re = ar * tc - as * ts, im = -(as * tc) - ar * ts;
;             bf16_t* op = A1 + (sbase + (size_t)ka * 128 + b) * 2048 + cb * 128 + 16 * w + 4 * lq;
;             u32x2 o; o.x = cvt_pk_bf16(re[0], re[1]); o.y = cvt_pk_bf16(re[2], re[3]); *(u32x2*)op = o;
;             o.x = cvt_pk_bf16(im[0], im[1]); o.y = cvt_pk_bf16(im[2], im[3]); *(u32x2*)(op + 1024) = o; }
	v_mfma_f32_16x16x32_bf16 v[52:55], v[14:17], v[52:55], 0
	s_waitcnt lgkmcnt(2)
	v_mfma_f32_16x16x32_bf16 v[56:59], v[14:17], v[56:59], 0
	s_waitcnt lgkmcnt(1)
	v_mfma_f32_16x16x32_bf16 v[52:55], v[10:13], v[60:63], v[52:55]
	s_waitcnt lgkmcnt(0)
	v_mfma_f32_16x16x32_bf16 v[56:59], v[10:13], v[64:67], v[56:59]
	ds_read_b128 v[60:63], v23 offset:128
	ds_read_b128 v[64:67], v23 offset:34944
	s_waitcnt lgkmcnt(1)
	v_mfma_f32_16x16x32_bf16 v[52:55], v[6:9], v[60:63], v[52:55]
	s_waitcnt lgkmcnt(0)
	v_mfma_f32_16x16x32_bf16 v[56:59], v[6:9], v[64:67], v[56:59]
	ds_read_b128 v[60:63], v23 offset:192
	ds_read_b128 v[64:67], v23 offset:35008
	s_waitcnt lgkmcnt(1)
	v_mfma_f32_16x16x32_bf16 v[52:55], v[2:5], v[60:63], v[52:55]
	v_mov_b32_e32 v61, s7
	v_or_b32_e32 v60, s6, v24
	v_lshlrev_b64 v[60:61], 12, v[60:61]
	s_waitcnt lgkmcnt(0)
	v_mfma_f32_16x16x32_bf16 v[56:59], v[2:5], v[64:67], v[56:59]
	v_lshl_add_u64 v[76:77], v[36:37], 0, v[60:61]
	ds_read_b128 v[60:63], v25
	ds_read_b128 v[64:67], v25 offset:34816
	ds_read_b128 v[68:71], v25 offset:64
	ds_read_b128 v[72:75], v25 offset:34880
	s_waitcnt lgkmcnt(3)
	v_mfma_f32_16x16x32_bf16 v[60:63], v[14:17], v[60:63], 0
	s_waitcnt lgkmcnt(2)
	v_mfma_f32_16x16x32_bf16 v[64:67], v[14:17], v[64:67], 0
	s_waitcnt lgkmcnt(1)
	v_mfma_f32_16x16x32_bf16 v[60:63], v[10:13], v[68:71], v[60:63]
	s_waitcnt lgkmcnt(0)
	v_mfma_f32_16x16x32_bf16 v[64:67], v[10:13], v[72:75], v[64:67]
	ds_read_b128 v[68:71], v25 offset:128
	ds_read_b128 v[72:75], v25 offset:34944
	s_waitcnt lgkmcnt(1)
	v_mfma_f32_16x16x32_bf16 v[60:63], v[6:9], v[68:71], v[60:63]
	s_waitcnt lgkmcnt(0)
	v_mfma_f32_16x16x32_bf16 v[64:67], v[6:9], v[72:75], v[64:67]
	ds_read_b128 v[68:71], v25 offset:192
	ds_read_b128 v[72:75], v25 offset:35008
	s_waitcnt lgkmcnt(1)
	v_mfma_f32_16x16x32_bf16 v[60:63], v[2:5], v[68:71], v[60:63]
	v_cvt_f32_u32_e32 v69, v79
	v_cvt_f32_u32_e32 v68, v78
	v_pk_mul_f32 v[68:69], v[68:69], s[14:15] op_sel_hi:[1,0]
	s_nop 0
	v_pk_mul_f32 v[70:71], v[68:69], 0.5 op_sel_hi:[1,0]
	s_waitcnt lgkmcnt(0)
	v_mfma_f32_16x16x32_bf16 v[64:67], v[2:5], v[72:75], v[64:67]
	v_fract_f32_e32 v72, v71
	v_add_f32_e32 v72, v72, v72
	v_cmp_neq_f32_e32 vcc, s10, v71
	s_nop 1
	v_cndmask_b32_e32 v71, 0, v72, vcc
	v_cmp_lt_f32_e32 vcc, 1.0, v69
	s_nop 1
	v_cndmask_b32_e32 v71, v69, v71, vcc
	v_add_f32_e32 v72, v71, v71
	v_rndne_f32_e32 v72, v72
	v_fmac_f32_e32 v71, -0.5, v72
	v_mul_f32_e32 v73, v71, v71
	v_fmamk_f32 v74, v73, 0x3e75aa41, v82
	v_fmaak_f32 v74, v73, v74, 0x40234736
	v_fmaak_f32 v74, v73, v74, 0xc0a55e0e
	v_mul_f32_e32 v75, v71, v73
	v_mul_f32_e32 v74, v75, v74
	v_cvt_i32_f32_e32 v72, v72
	v_fmac_f32_e32 v74, 0x40490fdb, v71
	v_fmamk_f32 v71, v73, 0x3d4be544, v83
	v_fmaak_f32 v71, v73, v71, 0xbfaad1da
	v_fmaak_f32 v71, v73, v71, 0x4081e0d3
	v_fmaak_f32 v71, v73, v71, 0xc09de9e6
	v_fma_f32 v71, v73, v71, 1.0
	v_lshlrev_b32_e32 v73, 30, v72
	v_and_b32_e32 v72, 1, v72
	v_cmp_eq_u32_e32 vcc, 0, v72
	s_nop 1
	v_cndmask_b32_e32 v72, v71, v74, vcc
	v_bitop3_b32 v75, v72, v73, s11 bitop3:0x78
	v_xor_b32_e32 v72, 0x80000000, v74
	v_cndmask_b32_e32 v71, v72, v71, vcc
	v_cmp_lg_f32_e32 vcc, s10, v69
	v_bitop3_b32 v71, v71, v73, s11 bitop3:0x78
	s_nop 0
	v_cndmask_b32_e32 v74, v84, v75, vcc
	v_cndmask_b32_e32 v72, v84, v71, vcc
	v_pk_mul_f32 v[78:79], v[74:75], v[56:57] op_sel_hi:[0,1]
	v_pk_mul_f32 v[80:81], v[74:75], v[58:59] op_sel_hi:[0,1]
	v_pk_fma_f32 v[80:81], v[72:73], v[54:55], v[80:81] op_sel_hi:[0,1,1] neg_lo:[0,0,1] neg_hi:[0,0,1]
	v_pk_fma_f32 v[78:79], v[72:73], v[52:53], v[78:79] op_sel_hi:[0,1,1] neg_lo:[0,0,1] neg_hi:[0,0,1]
	v_pk_mul_f32 v[52:53], v[74:75], v[52:53] op_sel_hi:[0,1]
	v_pk_mul_f32 v[54:55], v[74:75], v[54:55] op_sel_hi:[0,1]
	v_pk_fma_f32 v[54:55], v[58:59], v[72:73], v[54:55] op_sel_hi:[1,0,1] neg_lo:[0,1,1] neg_hi:[0,1,1]
	v_pk_fma_f32 v[52:53], v[56:57], v[72:73], v[52:53] op_sel_hi:[1,0,1] neg_lo:[0,1,1] neg_hi:[0,1,1]
	v_cmp_neq_f32_e32 vcc, s10, v70
	v_cvt_pk_bf16_f32 v52, v52, v53
	v_cvt_pk_bf16_f32 v53, v54, v55
	ds_write_b64 v232, v[52:53] offset:43520
	v_fract_f32_e32 v52, v70
	v_add_f32_e32 v52, v52, v52
	v_cndmask_b32_e32 v52, 0, v52, vcc
	v_cmp_lt_f32_e32 vcc, 1.0, v68
	v_cvt_pk_bf16_f32 v56, v78, v79
	v_cvt_pk_bf16_f32 v57, v80, v81
	v_cndmask_b32_e32 v52, v68, v52, vcc
	v_add_f32_e32 v53, v52, v52
	v_rndne_f32_e32 v53, v53
	v_fmac_f32_e32 v52, -0.5, v53
	v_mul_f32_e32 v54, v52, v52
	v_fmamk_f32 v55, v54, 0x3e75aa41, v82
	v_fmaak_f32 v55, v54, v55, 0x40234736
	ds_write_b64 v232, v[56:57] offset:8704
	v_fmaak_f32 v55, v54, v55, 0xc0a55e0e
	v_mul_f32_e32 v56, v52, v54
	v_mul_f32_e32 v55, v56, v55
	v_cvt_i32_f32_e32 v53, v53
	v_fmac_f32_e32 v55, 0x40490fdb, v52
	v_fmamk_f32 v52, v54, 0x3d4be544, v83
	v_fmaak_f32 v52, v54, v52, 0xbfaad1da
	v_fmaak_f32 v52, v54, v52, 0x4081e0d3
	v_fmaak_f32 v52, v54, v52, 0xc09de9e6
	v_fma_f32 v52, v54, v52, 1.0
	v_lshlrev_b32_e32 v54, 30, v53
	v_and_b32_e32 v53, 1, v53
	v_cmp_eq_u32_e32 vcc, 0, v53
	v_mul_u32_u24_e32 v78, s21, v45
	v_mul_u32_u24_e32 v79, s21, v46
	v_cndmask_b32_e32 v53, v52, v55, vcc
	v_xor_b32_e32 v55, 0x80000000, v55
	v_bitop3_b32 v53, v53, v54, s11 bitop3:0x78
	v_cndmask_b32_e32 v52, v55, v52, vcc
	v_cmp_lg_f32_e32 vcc, s10, v68
	v_bitop3_b32 v52, v52, v54, s11 bitop3:0x78
	s_nop 0
	v_cndmask_b32_e32 v54, v84, v53, vcc
	v_cndmask_b32_e32 v52, v84, v52, vcc
	v_pk_mul_f32 v[56:57], v[54:55], v[64:65] op_sel_hi:[0,1]
	v_pk_mul_f32 v[58:59], v[54:55], v[66:67] op_sel_hi:[0,1]
	v_pk_fma_f32 v[56:57], v[52:53], v[60:61], v[56:57] op_sel_hi:[0,1,1] neg_lo:[0,0,1] neg_hi:[0,0,1]
	v_pk_mul_f32 v[60:61], v[54:55], v[60:61] op_sel_hi:[0,1]
	v_pk_mul_f32 v[54:55], v[54:55], v[62:63] op_sel_hi:[0,1]
	v_pk_fma_f32 v[58:59], v[52:53], v[62:63], v[58:59] op_sel_hi:[0,1,1] neg_lo:[0,0,1] neg_hi:[0,0,1]
	v_pk_fma_f32 v[54:55], v[66:67], v[52:53], v[54:55] op_sel_hi:[1,0,1] neg_lo:[0,1,1] neg_hi:[0,1,1]
	v_pk_fma_f32 v[52:53], v[64:65], v[52:53], v[60:61] op_sel_hi:[1,0,1] neg_lo:[0,1,1] neg_hi:[0,1,1]
	v_mov_b32_e32 v61, s7
	v_or_b32_e32 v60, s6, v26
	v_lshlrev_b64 v[60:61], 12, v[60:61]
	v_lshl_add_u64 v[60:61], v[36:37], 0, v[60:61]
	v_cvt_pk_bf16_f32 v56, v56, v57
	v_cvt_pk_bf16_f32 v57, v58, v59
	v_cvt_pk_bf16_f32 v52, v52, v53
	v_cvt_pk_bf16_f32 v53, v54, v55
	ds_write_b64 v232, v[56:57] offset:13056
	ds_write_b64 v232, v[52:53] offset:47872
	ds_read_b128 v[52:55], v27
	ds_read_b128 v[56:59], v27 offset:34816
	ds_read_b128 v[60:63], v27 offset:64
	ds_read_b128 v[64:67], v27 offset:34880
	s_waitcnt lgkmcnt(3)
; __device__ __forceinline__ unsigned cvt_pk_bf16(float lo, float hi) { const f2_t v = {lo, hi}; const bf2_t b = __builtin_convertvector(v, bf2_t); return __builtin_bit_cast(unsigned, b); }
; __device__ __forceinline__ f32x4 mfma16(bf16x8 a, bf16x8 b, f32x4 c) { return __builtin_amdgcn_mfma_f32_16x16x32_bf16(a, b, c, 0, 0, 0); }
; template <int N1> __device__ void fft1_units(int wv, const Params& p, unsigned char* lds, int seq_lo, int nseq, int part, int nparts) {
;     ...
;         for (int i = 0; i < NB; ++i) { f32x4 ar = {0, 0, 0, 0}, as = {0, 0, 0, 0};
; #pragma unroll
;             for (int kk = 0; kk < NK; ++kk) { const bf16x8 cf = *(const bf16x8*)(CT + (16 * i + lr) * PW + 32 * kk + 8 * lq), sf = *(const bf16x8*)(ST + (16 * i + lr) * PW + 32 * kk + 8 * lq);
;                 ar = mfma16(xf[kk], cf, ar); as = mfma16(xf[kk], sf, as); }
;             const int ka = 16 * i + lr; float tc, ts; sincospif(2.0f * (float)(b * ka) / (float)S, &ts, &tc);
;             const f32x4 re = ar * tc - as * ts, im = -(as * tc) - ar * ts;
;             bf16_t* op = A1 + (sbase + (size_t)ka * 128 + b) * 2048 + cb * 128 + 16 * w + 4 * lq;
;             u32x2 o; o.x = cvt_pk_bf16(re[0], re[1]); o.y = cvt_pk_bf16(re[2], re[3]); *(u32x2*)op = o;
;             o.x = cvt_pk_bf16(im[0], im[1]); o.y = cvt_pk_bf16(im[2], im[3]); *(u32x2*)(op + 1024) = o; }
	v_mfma_f32_16x16x32_bf16 v[52:55], v[14:17], v[52:55], 0
	s_waitcnt lgkmcnt(2)
	v_mfma_f32_16x16x32_bf16 v[56:59], v[14:17], v[56:59], 0
	s_waitcnt lgkmcnt(1)
	v_mfma_f32_16x16x32_bf16 v[52:55], v[10:13], v[60:63], v[52:55]
	s_waitcnt lgkmcnt(0)
	v_mfma_f32_16x16x32_bf16 v[56:59], v[10:13], v[64:67], v[56:59]
	ds_read_b128 v[60:63], v27 offset:128
	ds_read_b128 v[64:67], v27 offset:34944
	s_waitcnt lgkmcnt(1)
	v_mfma_f32_16x16x32_bf16 v[52:55], v[6:9], v[60:63], v[52:55]
	s_waitcnt lgkmcnt(0)
	v_mfma_f32_16x16x32_bf16 v[56:59], v[6:9], v[64:67], v[56:59]
	ds_read_b128 v[60:63], v27 offset:192
	ds_read_b128 v[64:67], v27 offset:35008
	s_waitcnt lgkmcnt(1)
	v_mfma_f32_16x16x32_bf16 v[52:55], v[2:5], v[60:63], v[52:55]
	v_lshl_add_u64 v[60:61], s[6:7], 0, v[28:29]
	v_lshlrev_b64 v[60:61], 12, v[60:61]
	v_lshl_add_u64 v[76:77], v[36:37], 0, v[60:61]
	s_waitcnt lgkmcnt(0)
	v_mfma_f32_16x16x32_bf16 v[56:59], v[2:5], v[64:67], v[56:59]
	ds_read_b128 v[60:63], v38
	ds_read_b128 v[64:67], v38 offset:34816
	ds_read_b128 v[68:71], v38 offset:64
	ds_read_b128 v[72:75], v38 offset:34880
	s_waitcnt lgkmcnt(3)
	v_mfma_f32_16x16x32_bf16 v[60:63], v[14:17], v[60:63], 0
	s_waitcnt lgkmcnt(2)
	v_mfma_f32_16x16x32_bf16 v[64:67], v[14:17], v[64:67], 0
	s_waitcnt lgkmcnt(1)
	v_mfma_f32_16x16x32_bf16 v[60:63], v[10:13], v[68:71], v[60:63]
	s_waitcnt lgkmcnt(0)
	v_mfma_f32_16x16x32_bf16 v[64:67], v[10:13], v[72:75], v[64:67]
	ds_read_b128 v[68:71], v38 offset:128
	ds_read_b128 v[72:75], v38 offset:34944
	s_waitcnt lgkmcnt(1)
	v_mfma_f32_16x16x32_bf16 v[60:63], v[6:9], v[68:71], v[60:63]
	s_waitcnt lgkmcnt(0)
	v_mfma_f32_16x16x32_bf16 v[64:67], v[6:9], v[72:75], v[64:67]
	ds_read_b128 v[68:71], v38 offset:192
	ds_read_b128 v[72:75], v38 offset:35008
	s_waitcnt lgkmcnt(1)
	v_mfma_f32_16x16x32_bf16 v[60:63], v[2:5], v[68:71], v[60:63]
	v_cvt_f32_u32_e32 v69, v79
	v_cvt_f32_u32_e32 v68, v78
	v_pk_mul_f32 v[68:69], v[68:69], s[14:15] op_sel_hi:[1,0]
	s_nop 0
	v_pk_mul_f32 v[70:71], v[68:69], 0.5 op_sel_hi:[1,0]
	s_waitcnt lgkmcnt(0)
	v_mfma_f32_16x16x32_bf16 v[64:67], v[2:5], v[72:75], v[64:67]
	v_fract_f32_e32 v72, v71
	v_add_f32_e32 v72, v72, v72
	v_cmp_neq_f32_e32 vcc, s10, v71
	s_nop 1
	v_cndmask_b32_e32 v71, 0, v72, vcc
	v_cmp_lt_f32_e32 vcc, 1.0, v69
	s_nop 1
	v_cndmask_b32_e32 v71, v69, v71, vcc
	v_add_f32_e32 v72, v71, v71
	v_rndne_f32_e32 v72, v72
	v_fmac_f32_e32 v71, -0.5, v72
	v_mul_f32_e32 v73, v71, v71
	v_fmamk_f32 v74, v73, 0x3e75aa41, v82
	v_fmaak_f32 v74, v73, v74, 0x40234736
	v_fmaak_f32 v74, v73, v74, 0xc0a55e0e
	v_mul_f32_e32 v75, v71, v73
	v_mul_f32_e32 v74, v75, v74
	v_cvt_i32_f32_e32 v72, v72
	v_fmac_f32_e32 v74, 0x40490fdb, v71
	v_fmamk_f32 v71, v73, 0x3d4be544, v83
	v_fmaak_f32 v71, v73, v71, 0xbfaad1da
	v_fmaak_f32 v71, v73, v71, 0x4081e0d3
	v_fmaak_f32 v71, v73, v71, 0xc09de9e6
	v_fma_f32 v71, v73, v71, 1.0
	v_lshlrev_b32_e32 v73, 30, v72
	v_and_b32_e32 v72, 1, v72
	v_cmp_eq_u32_e32 vcc, 0, v72
	s_nop 1
	v_cndmask_b32_e32 v72, v71, v74, vcc
	v_bitop3_b32 v75, v72, v73, s11 bitop3:0x78
	v_xor_b32_e32 v72, 0x80000000, v74
	v_cndmask_b32_e32 v71, v72, v71, vcc
	v_cmp_lg_f32_e32 vcc, s10, v69
	v_bitop3_b32 v71, v71, v73, s11 bitop3:0x78
	s_nop 0
	v_cndmask_b32_e32 v74, v84, v75, vcc
	v_cndmask_b32_e32 v72, v84, v71, vcc
	v_pk_mul_f32 v[78:79], v[74:75], v[56:57] op_sel_hi:[0,1]
	v_pk_mul_f32 v[80:81], v[74:75], v[58:59] op_sel_hi:[0,1]
	v_pk_fma_f32 v[80:81], v[72:73], v[54:55], v[80:81] op_sel_hi:[0,1,1] neg_lo:[0,0,1] neg_hi:[0,0,1]
	v_pk_fma_f32 v[78:79], v[72:73], v[52:53], v[78:79] op_sel_hi:[0,1,1] neg_lo:[0,0,1] neg_hi:[0,0,1]
	v_pk_mul_f32 v[52:53], v[74:75], v[52:53] op_sel_hi:[0,1]
	v_pk_mul_f32 v[54:55], v[74:75], v[54:55] op_sel_hi:[0,1]
	v_pk_fma_f32 v[54:55], v[58:59], v[72:73], v[54:55] op_sel_hi:[1,0,1] neg_lo:[0,1,1] neg_hi:[0,1,1]
	v_pk_fma_f32 v[52:53], v[56:57], v[72:73], v[52:53] op_sel_hi:[1,0,1] neg_lo:[0,1,1] neg_hi:[0,1,1]
	v_cmp_neq_f32_e32 vcc, s10, v70
	v_cvt_pk_bf16_f32 v52, v52, v53
	v_cvt_pk_bf16_f32 v53, v54, v55
	ds_write_b64 v232, v[52:53] offset:52224
	v_fract_f32_e32 v52, v70
	v_add_f32_e32 v52, v52, v52
	v_cndmask_b32_e32 v52, 0, v52, vcc
	v_cmp_lt_f32_e32 vcc, 1.0, v68
	v_cvt_pk_bf16_f32 v56, v78, v79
	v_cvt_pk_bf16_f32 v57, v80, v81
	v_cndmask_b32_e32 v52, v68, v52, vcc
	v_add_f32_e32 v53, v52, v52
	v_rndne_f32_e32 v53, v53
	v_fmac_f32_e32 v52, -0.5, v53
	v_mul_f32_e32 v54, v52, v52
	v_fmamk_f32 v55, v54, 0x3e75aa41, v82
	v_fmaak_f32 v55, v54, v55, 0x40234736
	ds_write_b64 v232, v[56:57] offset:17408
	v_fmaak_f32 v55, v54, v55, 0xc0a55e0e
	v_mul_f32_e32 v56, v52, v54
	v_mul_f32_e32 v55, v56, v55
	v_cvt_i32_f32_e32 v53, v53
	v_fmac_f32_e32 v55, 0x40490fdb, v52
	v_fmamk_f32 v52, v54, 0x3d4be544, v83
	v_fmaak_f32 v52, v54, v52, 0xbfaad1da
	v_fmaak_f32 v52, v54, v52, 0x4081e0d3
	v_fmaak_f32 v52, v54, v52, 0xc09de9e6
	v_fma_f32 v52, v54, v52, 1.0
	v_lshlrev_b32_e32 v54, 30, v53
	v_and_b32_e32 v53, 1, v53
	v_cmp_eq_u32_e32 vcc, 0, v53
	v_mul_u32_u24_e32 v74, s21, v47
	v_mul_u32_u24_e32 v75, s21, v48
	v_cndmask_b32_e32 v53, v52, v55, vcc
	v_xor_b32_e32 v55, 0x80000000, v55
	v_bitop3_b32 v53, v53, v54, s11 bitop3:0x78
	v_cndmask_b32_e32 v52, v55, v52, vcc
	v_cmp_lg_f32_e32 vcc, s10, v68
	v_bitop3_b32 v52, v52, v54, s11 bitop3:0x78
	s_nop 0
	v_cndmask_b32_e32 v54, v84, v53, vcc
	v_cndmask_b32_e32 v52, v84, v52, vcc
	v_pk_mul_f32 v[56:57], v[54:55], v[64:65] op_sel_hi:[0,1]
	v_pk_mul_f32 v[58:59], v[54:55], v[66:67] op_sel_hi:[0,1]
	v_pk_fma_f32 v[56:57], v[52:53], v[60:61], v[56:57] op_sel_hi:[0,1,1] neg_lo:[0,0,1] neg_hi:[0,0,1]
	v_pk_mul_f32 v[60:61], v[54:55], v[60:61] op_sel_hi:[0,1]
	v_pk_mul_f32 v[54:55], v[54:55], v[62:63] op_sel_hi:[0,1]
	v_pk_fma_f32 v[58:59], v[52:53], v[62:63], v[58:59] op_sel_hi:[0,1,1] neg_lo:[0,0,1] neg_hi:[0,0,1]
	v_pk_fma_f32 v[54:55], v[66:67], v[52:53], v[54:55] op_sel_hi:[1,0,1] neg_lo:[0,1,1] neg_hi:[0,1,1]
	v_pk_fma_f32 v[52:53], v[64:65], v[52:53], v[60:61] op_sel_hi:[1,0,1] neg_lo:[0,1,1] neg_hi:[0,1,1]
	v_lshl_add_u64 v[60:61], s[6:7], 0, v[30:31]
	v_lshlrev_b64 v[60:61], 12, v[60:61]
	v_lshl_add_u64 v[60:61], v[36:37], 0, v[60:61]
	v_cvt_pk_bf16_f32 v56, v56, v57
	v_cvt_pk_bf16_f32 v57, v58, v59
	v_cvt_pk_bf16_f32 v52, v52, v53
	v_cvt_pk_bf16_f32 v53, v54, v55
	ds_write_b64 v232, v[56:57] offset:21760
	ds_write_b64 v232, v[52:53] offset:56576
	ds_read_b128 v[52:55], v39
	ds_read_b128 v[56:59], v39 offset:34816
	ds_read_b128 v[60:63], v39 offset:64
	ds_read_b128 v[64:67], v39 offset:34880
	s_waitcnt lgkmcnt(3)
; __device__ __forceinline__ unsigned cvt_pk_bf16(float lo, float hi) { const f2_t v = {lo, hi}; const bf2_t b = __builtin_convertvector(v, bf2_t); return __builtin_bit_cast(unsigned, b); }
; __device__ __forceinline__ f32x4 mfma16(bf16x8 a, bf16x8 b, f32x4 c) { return __builtin_amdgcn_mfma_f32_16x16x32_bf16(a, b, c, 0, 0, 0); }
; template <int N1> __device__ void fft1_units(int wv, const Params& p, unsigned char* lds, int seq_lo, int nseq, int part, int nparts) {
;     ...
;         for (int i = 0; i < NB; ++i) { f32x4 ar = {0, 0, 0, 0}, as = {0, 0, 0, 0};
; #pragma unroll
;             for (int kk = 0; kk < NK; ++kk) { const bf16x8 cf = *(const bf16x8*)(CT + (16 * i + lr) * PW + 32 * kk + 8 * lq), sf = *(const bf16x8*)(ST + (16 * i + lr) * PW + 32 * kk + 8 * lq);
;                 ar = mfma16(xf[kk], cf, ar); as = mfma16(xf[kk], sf, as); }
;             const int ka = 16 * i + lr; float tc, ts; sincospif(2.0f * (float)(b * ka) / (float)S, &ts, &tc);
;             const f32x4 re = ar * tc - as * ts, im = -(as * tc) - ar * ts;
;             bf16_t* op = A1 + (sbase + (size_t)ka * 128 + b) * 2048 + cb * 128 + 16 * w + 4 * lq;
;             u32x2 o; o.x = cvt_pk_bf16(re[0], re[1]); o.y = cvt_pk_bf16(re[2], re[3]); *(u32x2*)op = o;
;             o.x = cvt_pk_bf16(im[0], im[1]); o.y = cvt_pk_bf16(im[2], im[3]); *(u32x2*)(op + 1024) = o; }
;         __syncthreads();
	v_mfma_f32_16x16x32_bf16 v[52:55], v[14:17], v[52:55], 0
	s_waitcnt lgkmcnt(2)
	v_mfma_f32_16x16x32_bf16 v[56:59], v[14:17], v[56:59], 0
	s_waitcnt lgkmcnt(1)
	v_mfma_f32_16x16x32_bf16 v[52:55], v[10:13], v[60:63], v[52:55]
	s_waitcnt lgkmcnt(0)
	v_mfma_f32_16x16x32_bf16 v[56:59], v[10:13], v[64:67], v[56:59]
	ds_read_b128 v[60:63], v39 offset:128
	ds_read_b128 v[64:67], v39 offset:34944
	s_waitcnt lgkmcnt(1)
	v_mfma_f32_16x16x32_bf16 v[52:55], v[6:9], v[60:63], v[52:55]
	s_waitcnt lgkmcnt(0)
	v_mfma_f32_16x16x32_bf16 v[56:59], v[6:9], v[64:67], v[56:59]
	ds_read_b128 v[60:63], v39 offset:192
	ds_read_b128 v[64:67], v39 offset:35008
	s_waitcnt lgkmcnt(1)
	v_mfma_f32_16x16x32_bf16 v[52:55], v[2:5], v[60:63], v[52:55]
	v_lshl_add_u64 v[60:61], s[6:7], 0, v[32:33]
	v_lshlrev_b64 v[60:61], 12, v[60:61]
	v_lshl_add_u64 v[72:73], v[36:37], 0, v[60:61]
	s_waitcnt lgkmcnt(0)
	v_mfma_f32_16x16x32_bf16 v[56:59], v[2:5], v[64:67], v[56:59]
	ds_read_b128 v[60:63], v40
	ds_read_b128 v[64:67], v40 offset:34816
	s_waitcnt lgkmcnt(1)
	v_mfma_f32_16x16x32_bf16 v[60:63], v[14:17], v[60:63], 0
	s_waitcnt lgkmcnt(0)
	v_mfma_f32_16x16x32_bf16 v[14:17], v[14:17], v[64:67], 0
	ds_read_b128 v[64:67], v40 offset:64
	ds_read_b128 v[68:71], v40 offset:34880
	s_waitcnt lgkmcnt(1)
	v_mfma_f32_16x16x32_bf16 v[60:63], v[10:13], v[64:67], v[60:63]
	s_waitcnt lgkmcnt(0)
	v_mfma_f32_16x16x32_bf16 v[10:13], v[10:13], v[68:71], v[14:17]
	s_nop 2
	ds_read_b128 v[14:17], v40 offset:128
	ds_read_b128 v[64:67], v40 offset:34944
	s_waitcnt lgkmcnt(1)
	v_mfma_f32_16x16x32_bf16 v[14:17], v[6:9], v[14:17], v[60:63]
	s_waitcnt lgkmcnt(0)
	v_mfma_f32_16x16x32_bf16 v[6:9], v[6:9], v[64:67], v[10:13]
	s_nop 2
	ds_read_b128 v[10:13], v40 offset:192
	ds_read_b128 v[60:63], v40 offset:35008
	s_waitcnt lgkmcnt(1)
	v_mfma_f32_16x16x32_bf16 v[10:13], v[2:5], v[10:13], v[14:17]
	s_waitcnt lgkmcnt(0)
	v_mfma_f32_16x16x32_bf16 v[2:5], v[2:5], v[60:63], v[6:9]
	s_nop 2
	v_cvt_f32_u32_e32 v7, v75
	v_cvt_f32_u32_e32 v6, v74
	v_pk_mul_f32 v[6:7], v[6:7], s[14:15] op_sel_hi:[1,0]
	s_nop 0
	v_pk_mul_f32 v[8:9], v[6:7], 0.5 op_sel_hi:[1,0]
	s_nop 0
	v_fract_f32_e32 v14, v9
	v_add_f32_e32 v14, v14, v14
	v_cmp_neq_f32_e32 vcc, s10, v9
	s_nop 1
	v_cndmask_b32_e32 v9, 0, v14, vcc
	v_cmp_lt_f32_e32 vcc, 1.0, v7
	s_nop 1
	v_cndmask_b32_e32 v9, v7, v9, vcc
	v_add_f32_e32 v14, v9, v9
	v_rndne_f32_e32 v14, v14
	v_fmac_f32_e32 v9, -0.5, v14
	v_mul_f32_e32 v15, v9, v9
	v_fmamk_f32 v16, v15, 0x3e75aa41, v82
	v_fmaak_f32 v16, v15, v16, 0x40234736
	v_fmaak_f32 v16, v15, v16, 0xc0a55e0e
	v_mul_f32_e32 v17, v9, v15
	v_mul_f32_e32 v16, v17, v16
	v_cvt_i32_f32_e32 v14, v14
	v_fmac_f32_e32 v16, 0x40490fdb, v9
	v_fmamk_f32 v9, v15, 0x3d4be544, v83
	v_fmaak_f32 v9, v15, v9, 0xbfaad1da
	v_fmaak_f32 v9, v15, v9, 0x4081e0d3
	v_fmaak_f32 v9, v15, v9, 0xc09de9e6
	v_fma_f32 v9, v15, v9, 1.0
	v_lshlrev_b32_e32 v15, 30, v14
	v_and_b32_e32 v14, 1, v14
	v_cmp_eq_u32_e32 vcc, 0, v14
	s_nop 1
	v_cndmask_b32_e32 v14, v9, v16, vcc
	v_bitop3_b32 v17, v14, v15, s11 bitop3:0x78
	v_xor_b32_e32 v14, 0x80000000, v16
	v_cndmask_b32_e32 v9, v14, v9, vcc
	v_bitop3_b32 v9, v9, v15, s11 bitop3:0x78
	v_cmp_lg_f32_e32 vcc, s10, v7
	v_fract_f32_e32 v7, v8
	v_add_f32_e32 v7, v7, v7
	v_cndmask_b32_e32 v14, v84, v9, vcc
	v_cndmask_b32_e32 v16, v84, v17, vcc
	v_cmp_neq_f32_e32 vcc, s10, v8
	v_pk_mul_f32 v[60:61], v[16:17], v[56:57] op_sel_hi:[0,1]
	v_pk_mul_f32 v[62:63], v[16:17], v[58:59] op_sel_hi:[0,1]
	v_cndmask_b32_e32 v7, 0, v7, vcc
	v_cmp_lt_f32_e32 vcc, 1.0, v6
	v_pk_fma_f32 v[60:61], v[14:15], v[52:53], v[60:61] op_sel_hi:[0,1,1] neg_lo:[0,0,1] neg_hi:[0,0,1]
	v_pk_mul_f32 v[52:53], v[16:17], v[52:53] op_sel_hi:[0,1]
	v_cndmask_b32_e32 v7, v6, v7, vcc
	v_add_f32_e32 v8, v7, v7
	v_pk_mul_f32 v[16:17], v[16:17], v[54:55] op_sel_hi:[0,1]
	v_rndne_f32_e32 v8, v8
	v_pk_fma_f32 v[62:63], v[14:15], v[54:55], v[62:63] op_sel_hi:[0,1,1] neg_lo:[0,0,1] neg_hi:[0,0,1]
	v_pk_fma_f32 v[16:17], v[58:59], v[14:15], v[16:17] op_sel_hi:[1,0,1] neg_lo:[0,1,1] neg_hi:[0,1,1]
	v_pk_fma_f32 v[14:15], v[56:57], v[14:15], v[52:53] op_sel_hi:[1,0,1] neg_lo:[0,1,1] neg_hi:[0,1,1]
	v_fmac_f32_e32 v7, -0.5, v8
	v_cvt_pk_bf16_f32 v14, v14, v15
	v_cvt_pk_bf16_f32 v15, v16, v17
	v_mul_f32_e32 v9, v7, v7
	ds_write_b64 v232, v[14:15] offset:60928
	v_fmamk_f32 v14, v9, 0x3e75aa41, v82
	v_fmaak_f32 v14, v9, v14, 0x40234736
	v_fmaak_f32 v14, v9, v14, 0xc0a55e0e
	v_mul_f32_e32 v15, v7, v9
	v_mul_f32_e32 v14, v15, v14
	v_cvt_i32_f32_e32 v8, v8
	v_fmac_f32_e32 v14, 0x40490fdb, v7
	v_fmamk_f32 v7, v9, 0x3d4be544, v83
	v_fmaak_f32 v7, v9, v7, 0xbfaad1da
	v_fmaak_f32 v7, v9, v7, 0x4081e0d3
	v_fmaak_f32 v7, v9, v7, 0xc09de9e6
	v_fma_f32 v7, v9, v7, 1.0
	v_lshlrev_b32_e32 v9, 30, v8
	v_and_b32_e32 v8, 1, v8
	v_cmp_eq_u32_e32 vcc, 0, v8
	v_cvt_pk_bf16_f32 v52, v60, v61
	v_cvt_pk_bf16_f32 v53, v62, v63
	v_cndmask_b32_e32 v8, v7, v14, vcc
	v_xor_b32_e32 v14, 0x80000000, v14
	v_bitop3_b32 v8, v8, v9, s11 bitop3:0x78
	v_cndmask_b32_e32 v7, v14, v7, vcc
	v_cmp_lg_f32_e32 vcc, s10, v6
	v_bitop3_b32 v7, v7, v9, s11 bitop3:0x78
	ds_write_b64 v232, v[52:53] offset:26112
	v_cndmask_b32_e32 v8, v84, v8, vcc
	v_cndmask_b32_e32 v6, v84, v7, vcc
	v_pk_mul_f32 v[14:15], v[8:9], v[2:3] op_sel_hi:[0,1]
	v_pk_mul_f32 v[16:17], v[8:9], v[4:5] op_sel_hi:[0,1]
	v_pk_fma_f32 v[14:15], v[6:7], v[10:11], v[14:15] op_sel_hi:[0,1,1] neg_lo:[0,0,1] neg_hi:[0,0,1]
	v_pk_mul_f32 v[10:11], v[8:9], v[10:11] op_sel_hi:[0,1]
	v_pk_mul_f32 v[8:9], v[8:9], v[12:13] op_sel_hi:[0,1]
	v_pk_fma_f32 v[16:17], v[6:7], v[12:13], v[16:17] op_sel_hi:[0,1,1] neg_lo:[0,0,1] neg_hi:[0,0,1]
	v_pk_fma_f32 v[4:5], v[4:5], v[6:7], v[8:9] op_sel_hi:[1,0,1] neg_lo:[0,1,1] neg_hi:[0,1,1]
	v_pk_fma_f32 v[2:3], v[2:3], v[6:7], v[10:11] op_sel_hi:[1,0,1] neg_lo:[0,1,1] neg_hi:[0,1,1]
	v_lshl_add_u64 v[6:7], s[6:7], 0, v[34:35]
	v_lshlrev_b64 v[6:7], 12, v[6:7]
	v_lshl_add_u64 v[6:7], v[36:37], 0, v[6:7]
	v_cvt_pk_bf16_f32 v8, v14, v15
	v_cvt_pk_bf16_f32 v9, v16, v17
	v_cvt_pk_bf16_f32 v2, v2, v3
	v_cvt_pk_bf16_f32 v3, v4, v5
	ds_write_b64 v232, v[8:9] offset:30464
	ds_write_b64 v232, v[2:3] offset:65280
	s_waitcnt lgkmcnt(0)
	s_barrier
; template <int N1> __device__ void fft1_units(int wv, const Params& p, unsigned char* lds, int seq_lo, int nseq, int part, int nparts) {
;     ...
;     for (int unit = part; unit < nunits; unit += nparts) {
;         const int sq = unit / 1024, b = (unit >> 3) & 127, cb = unit & 7;
;         const int seq = seq_lo + sq; const size_t sbase = (size_t)seq * 8192;
;         for (int idx = tid; idx < N1 * 16; idx += NTHR) { const int a = idx % N1, c8 = (idx / N1) * 8;
;             const bf16x8 v = *(const bf16x8*)(z + (sbase + 128 * a + b) * DM + cb * 128 + c8);
;     ...
;         __syncthreads();
	ds_read_b128 v[100:103], v233 offset:0
	ds_read_b128 v[104:107], v233 offset:34816
	ds_read_b128 v[108:111], v233 offset:8704
	ds_read_b128 v[112:115], v233 offset:43520
	ds_read_b128 v[116:119], v233 offset:17408
	ds_read_b128 v[120:123], v233 offset:52224
	ds_read_b128 v[124:127], v233 offset:26112
	ds_read_b128 v[128:131], v233 offset:60928
	s_mov_b64 s[14:15], 0x1000000
	v_mov_b32_e32 v236, v242
	v_mov_b32_e32 v237, v243
	s_waitcnt lgkmcnt(7)
	global_store_dwordx4 v[236:237], v[100:103], off
	s_waitcnt lgkmcnt(6)
	global_store_dwordx4 v[236:237], v[104:107], off offset:2048
	v_lshl_add_u64 v[236:237], v[236:237], 0, s[14:15]
	s_waitcnt lgkmcnt(5)
	global_store_dwordx4 v[236:237], v[108:111], off
	s_waitcnt lgkmcnt(4)
	global_store_dwordx4 v[236:237], v[112:115], off offset:2048
	v_lshl_add_u64 v[236:237], v[236:237], 0, s[14:15]
	s_waitcnt lgkmcnt(3)
	global_store_dwordx4 v[236:237], v[116:119], off
	s_waitcnt lgkmcnt(2)
	global_store_dwordx4 v[236:237], v[120:123], off offset:2048
	v_lshl_add_u64 v[236:237], v[236:237], 0, s[14:15]
	s_waitcnt lgkmcnt(1)
	global_store_dwordx4 v[236:237], v[124:127], off
	s_waitcnt lgkmcnt(0)
	global_store_dwordx4 v[236:237], v[128:131], off offset:2048
	s_barrier
	s_cmpk_gt_i32 s20, 0x3ff
	s_cbranch_scc1 .LBB0_319
.LBB0_316:
	s_ashr_i32 s6, s20, 31
	s_lshr_b32 s6, s6, 22
	s_add_i32 s6, s20, s6
	s_ashr_i32 s6, s6, 10
	s_ashr_i32 s7, s6, 31
	s_bfe_u32 s21, s20, 0x70003
	s_lshl_b64 s[6:7], s[6:7], 13
	s_or_b32 s6, s6, s21
	s_add_u32 s6, s6, 0x4000
	s_addc_u32 s7, s7, 0
	s_lshl_b32 s10, s20, 7
	s_and_b32 s22, s10, 0x380
	s_mov_b64 s[10:11], exec
	s_movk_i32 s36, 0x5ff
	s_lshl_b32 s14, s22, 1
	s_add_u32 s14, s76, s14
	s_addc_u32 s15, s77, 0
	s_lshl_b64 s[46:47], s[6:7], 12
	s_lshl_b32 s23, s22, 1
	s_add_u32 s46, s46, s23
	s_addc_u32 s47, s47, 0
	v_lshl_add_u64 v[242:243], s[46:47], 0, v[244:245]
	s_lshl_b64 s[16:17], s[6:7], 11
	s_add_u32 s14, s14, s16
	s_addc_u32 s15, s15, s17
	v_lshl_add_u64 v[204:205], s[14:15], 0, v[200:201]
	s_mov_b64 s[16:17], 0x800000
	global_load_dwordx4 v[206:209], v[204:205], off
	v_lshl_add_u64 v[204:205], v[204:205], 0, s[16:17]
	global_load_dwordx4 v[210:213], v[204:205], off
	v_lshl_add_u64 v[204:205], v[204:205], 0, s[16:17]
	global_load_dwordx4 v[214:217], v[204:205], off
	v_lshl_add_u64 v[204:205], v[204:205], 0, s[16:17]
	global_load_dwordx4 v[218:221], v[204:205], off
	s_waitcnt vmcnt(3)
	ds_write_b128 v202, v[206:209]
	s_waitcnt vmcnt(2)
	ds_write_b128 v202, v[210:213] offset:8192
	s_waitcnt vmcnt(1)
	ds_write_b128 v202, v[214:217] offset:16384
	s_waitcnt vmcnt(0)
	ds_write_b128 v202, v[218:221] offset:24576
	s_branch .LBB0_315

; __device__ __forceinline__ f32x4 mfma16(bf16x8 a, bf16x8 b, f32x4 c) { return __builtin_amdgcn_mfma_f32_16x16x32_bf16(a, b, c, 0, 0, 0); }
; template <int N1> __device__ void fft1_units(int wv, const Params& p, unsigned char* lds, int seq_lo, int nseq, int part, int nparts) {
;     const int tid = otid(wv), lane = tid & 63, w = __builtin_amdgcn_readfirstlane(tid >> 6), lr = lane & 15, lq = lane >> 4;
;     constexpr int PW = N1 + 8, NB = N1 / 16, NK = N1 / 32; constexpr int S = N1 * 128;
;     const bf16_t* z = (const bf16_t*)(p.ws + WS_BIG1); bf16_t* A1 = (bf16_t*)(p.ws + WS_BIG2);
;     const bf16_t* ctg = (const bf16_t*)(p.ws + WS_TAB + (N1 == 64 ? TAB_CT64 : TAB_CT128)); const bf16_t* stg = (const bf16_t*)(p.ws + WS_TAB + (N1 == 64 ? TAB_ST64 : TAB_ST128));
;     bf16_t* CT = (bf16_t*)lds; bf16_t* ST = CT + N1 * PW; bf16_t* XT = ST + N1 * PW;
;     for (int idx = tid; idx < N1 * N1 / 8; idx += NTHR) { const int r = idx / (N1 / 8), c8 = (idx % (N1 / 8)) * 8;
;         *(bf16x8*)(CT + r * PW + c8) = *(const bf16x8*)(ctg + r * N1 + c8); *(bf16x8*)(ST + r * PW + c8) = *(const bf16x8*)(stg + r * N1 + c8); }
;     __syncthreads();
;     const int nunits = nseq * 128 * 8;
;     for (int unit = part; unit < nunits; unit += nparts) {
;         const int sq = unit / 1024, b = (unit >> 3) & 127, cb = unit & 7;
;         const int seq = seq_lo + sq; const size_t sbase = (size_t)seq * 8192;
;         for (int idx = tid; idx < N1 * 16; idx += NTHR) { const int a = idx % N1, c8 = (idx / N1) * 8;
;             const bf16x8 v = *(const bf16x8*)(z + (sbase + 128 * a + b) * DM + cb * 128 + c8);
; #pragma unroll
;             for (int e = 0; e < 8; ++e) XT[(c8 + e) * PW + a] = (bf16_t)v[e]; }
;         __syncthreads();
;         bf16x8 xf[NK];
; #pragma unroll
;         for (int kk = 0; kk < NK; ++kk) xf[kk] = *(const bf16x8*)(XT + (16 * w + lr) * PW + 32 * kk + 8 * lq);
; #pragma unroll
;         for (int i = 0; i < NB; ++i) { f32x4 ar = {0, 0, 0, 0}, as = {0, 0, 0, 0};
; #pragma unroll
;             for (int kk = 0; kk < NK; ++kk) { const bf16x8 cf = *(const bf16x8*)(CT + (16 * i + lr) * PW + 32 * kk + 8 * lq), sf = *(const bf16x8*)(ST + (16 * i + lr) * PW + 32 * kk + 8 * lq);
;                 ar = mfma16(xf[kk], cf, ar); as = mfma16(xf[kk], sf, as); }
;             const int ka = 16 * i + lr; float tc, ts; sincospif(2.0f * (float)(b * ka) / (float)S, &ts, &tc);
.LBB0_324:
	s_or_b64 exec, exec, s[0:1]
	v_readlane_b32 s0, v254, 9
	v_readlane_b32 s1, v254, 10
	s_andn2_b64 vcc, exec, s[0:1]
	s_waitcnt lgkmcnt(0)
	s_barrier
	s_cbranch_vccnz .LBB0_333
	s_movk_i32 s0, 0x3ff
	s_ashr_i32 s1, s10, 2
	v_cmp_lt_i32_e32 vcc, s0, v1
	s_and_b32 s0, s1, -16
	v_bfi_b32 v3, -16, s1, v1
	s_movk_i32 s1, 0x90
	v_mul_lo_u32 v3, v3, s1
	s_ashr_i32 s1, s0, 31
	s_lshl_b64 s[0:1], s[0:1], 1
	v_readlane_b32 s6, v254, 13
	v_and_b32_e32 v4, 15, v1
	v_bfe_u32 v2, v1, 4, 2
	v_readlane_b32 s7, v254, 14
	s_add_u32 s0, s6, s0
	v_add_u32_e32 v5, 0, v3
	v_lshlrev_b32_e32 v6, 4, v2
	v_lshlrev_b32_e32 v2, 3, v2
	s_addc_u32 s1, s7, s1
	v_mov_b32_e32 v3, v0
	v_or_b32_e32 v18, 32, v4
	v_or_b32_e32 v17, 48, v4
	v_add_u32_e32 v7, 0, v6
	v_lshl_add_u64 v[2:3], s[0:1], 0, v[2:3]
	v_mul_u32_u24_e32 v8, 0x48, v4
	v_or_b32_e32 v15, 16, v4
	v_mul_u32_u24_e32 v11, 0x48, v18
	v_mul_u32_u24_e32 v13, 0x48, v17
	v_readlane_b32 s0, v254, 58
	v_lshl_add_u32 v8, v8, 1, v7
	v_lshlrev_b32_e32 v9, 7, v4
	v_lshlrev_b32_e32 v10, 7, v15
	v_lshl_add_u32 v11, v11, 1, v7
	v_lshlrev_b32_e32 v12, 7, v18
	v_lshl_add_u32 v13, v13, 1, v7
	v_lshlrev_b32_e32 v14, 7, v17
	v_lshlrev_b32_e32 v15, 1, v15
	v_lshlrev_b32_e32 v16, 1, v4
	v_lshlrev_b32_e32 v17, 1, v17
	v_lshlrev_b32_e32 v18, 1, v18
	v_lshlrev_b32_e32 v19, 7, v1
	v_lshl_add_u32 v20, v1, 1, s0
	v_add_u32_e32 v21, v5, v6
	s_mov_b32 s22, s2
	v_mbcnt_lo_u32_b32 v224, -1, 0
	v_mbcnt_hi_u32_b32 v224, -1, v224
	v_lshl_add_u32 v225, s33, 6, v224
	v_lshrrev_b32_e32 v226, 4, v225
	v_and_b32_e32 v227, 15, v225
	v_and_b32_e32 v228, 3, v226
	v_lshlrev_b32_e32 v228, 2, v228
	v_bfe_u32 v229, v226, 2, 2
	v_or_b32_e32 v228, v228, v229
	v_xor_b32_e32 v228, v227, v228
	v_lshlrev_b32_e32 v228, 4, v228
	v_lshl_add_u32 v202, v226, 8, v228
	v_add_u32_e32 v202, 0x4800, v202
	v_lshlrev_b32_e32 v200, 18, v226
	v_lshl_add_u32 v200, v227, 4, v200
	v_mov_b32_e32 v201, 0
	v_bfe_u32 v226, v224, 2, 2
	v_and_b32_e32 v227, 3, v224
	v_lshrrev_b32_e32 v228, 4, v224
	v_lshl_add_u32 v229, v228, 3, v226
	v_lshlrev_b32_e32 v230, 2, v226
	v_lshlrev_b32_e32 v228, 1, v228
	v_and_b32_e32 v231, 3, v228
	v_or_b32_e32 v231, v230, v231
	v_add_u32_e32 v228, 1, v228
	v_and_b32_e32 v228, 3, v228
	v_or_b32_e32 v228, v230, v228
	s_lshl_b32 s14, s33, 1
	v_lshrrev_b32_e32 v230, 1, v227
	v_add_u32_e32 v230, s14, v230
	v_and_b32_e32 v227, 1, v227
	v_lshlrev_b32_e32 v227, 3, v227
	v_xor_b32_e32 v231, v230, v231
	v_lshl_add_u32 v231, v231, 4, v227
	v_lshl_add_u32 v222, v229, 8, v231
	v_add_u32_e32 v222, 0x4800, v222
	v_xor_b32_e32 v228, v230, v228
	v_lshl_add_u32 v228, v228, 4, v227
	v_add_u32_e32 v229, 4, v229
	v_lshl_add_u32 v223, v229, 8, v228
	v_add_u32_e32 v223, 0x4800, v223
	v_and_b32_e32 v232, 15, v224
	v_mul_u32_u24_e32 v232, 0x110, v232
	v_lshrrev_b32_e32 v233, 4, v224
	v_lshl_add_u32 v232, v233, 3, v232
	s_lshl_b32 s14, s33, 5
	v_add_u32_e32 v232, s14, v232
	v_add_u32_e32 v232, 0x9000, v232
	v_lshrrev_b32_e32 v234, 4, v225
	v_and_b32_e32 v244, 15, v225
	v_lshlrev_b32_e32 v244, 4, v244
	v_mul_u32_u24_e32 v233, 0x110, v234
	v_add_u32_e32 v233, v233, v244
	v_add_u32_e32 v233, 0x9000, v233
	v_lshl_add_u32 v244, v234, 19, v244
	v_mov_b32_e32 v245, 0
	v_readlane_b32 s14, v254, 13
	v_readlane_b32 s15, v254, 14
	s_nop 0
	v_lshl_add_u64 v[244:245], s[14:15], 0, v[244:245]
	s_branch .LBB0_327
.LBB0_326:
	s_or_b64 exec, exec, s[10:11]
	s_waitcnt lgkmcnt(0)
	s_barrier
	ds_read_b64_tr_b16 v[22:23], v222
	ds_read_b64_tr_b16 v[24:25], v223
	ds_read_b128 v[26:29], v8
	ds_read_b64_tr_b16 v[30:31], v222 offset:8192
	ds_read_b64_tr_b16 v[32:33], v223 offset:8192
	ds_read_b128 v[34:37], v8 offset:64
	ds_read_b128 v[38:41], v8 offset:9216
	ds_read_b128 v[42:45], v8 offset:9280
	s_waitcnt lgkmcnt(4)
	v_mfma_f32_16x16x32_bf16 v[26:29], v[22:25], v[26:29], 0
	v_mul_u32_u24_e32 v54, s23, v15
	v_mul_u32_u24_e32 v55, s23, v16
	v_cvt_f32_u32_e32 v55, v55
	s_waitcnt lgkmcnt(1)
	v_mfma_f32_16x16x32_bf16 v[38:41], v[22:25], v[38:41], 0
	v_cvt_f32_u32_e32 v54, v54
	s_mov_b32 s14, 0x39000000
	v_or_b32_e32 v6, s23, v9
	v_mfma_f32_16x16x32_bf16 v[26:29], v[30:33], v[34:37], v[26:29]
	ds_read_b128 v[34:37], v8 offset:2304
	v_or_b32_e32 v6, s6, v6
	v_mov_b32_e32 v7, s7
	s_waitcnt lgkmcnt(1)
	v_mfma_f32_16x16x32_bf16 v[38:41], v[30:33], v[42:45], v[38:41]
	ds_read_b128 v[42:45], v8 offset:11520
	ds_read_b128 v[46:49], v8 offset:2368
	ds_read_b128 v[50:53], v8 offset:11584
	s_mov_b32 s7, 0x7f800000
	s_waitcnt lgkmcnt(3)
	v_mfma_f32_16x16x32_bf16 v[34:37], v[22:25], v[34:37], 0
	v_mov_b32_e32 v58, 0xbf1f24be
	v_mov_b32_e32 v59, 0x3e642e9d
	s_brev_b32 s10, 1
	s_waitcnt lgkmcnt(2)
	v_mfma_f32_16x16x32_bf16 v[42:45], v[22:25], v[42:45], 0
	v_mov_b32_e32 v60, 0x7fc00000
	v_lshl_add_u64 v[4:5], v[4:5], 1, v[2:3]
	s_add_i32 s22, s22, s93
	s_waitcnt lgkmcnt(1)
	v_mfma_f32_16x16x32_bf16 v[34:37], v[30:33], v[46:49], v[34:37]
	v_mul_f32_e64 v48, v54, s14
	v_mul_f32_e64 v49, v55, s14
	v_lshlrev_b64 v[46:47], 12, v[6:7]
	v_lshl_add_u64 v[46:47], v[4:5], 0, v[46:47]
	s_waitcnt lgkmcnt(0)
; __device__ __forceinline__ unsigned cvt_pk_bf16(float lo, float hi) { const f2_t v = {lo, hi}; const bf2_t b = __builtin_convertvector(v, bf2_t); return __builtin_bit_cast(unsigned, b); }
; __device__ __forceinline__ f32x4 mfma16(bf16x8 a, bf16x8 b, f32x4 c) { return __builtin_amdgcn_mfma_f32_16x16x32_bf16(a, b, c, 0, 0, 0); }
; template <int N1> __device__ void fft1_units(int wv, const Params& p, unsigned char* lds, int seq_lo, int nseq, int part, int nparts) {
;     ...
;         for (int i = 0; i < NB; ++i) { f32x4 ar = {0, 0, 0, 0}, as = {0, 0, 0, 0};
; #pragma unroll
;             for (int kk = 0; kk < NK; ++kk) { const bf16x8 cf = *(const bf16x8*)(CT + (16 * i + lr) * PW + 32 * kk + 8 * lq), sf = *(const bf16x8*)(ST + (16 * i + lr) * PW + 32 * kk + 8 * lq);
;                 ar = mfma16(xf[kk], cf, ar); as = mfma16(xf[kk], sf, as); }
;             const int ka = 16 * i + lr; float tc, ts; sincospif(2.0f * (float)(b * ka) / (float)S, &ts, &tc);
;             const f32x4 re = ar * tc - as * ts, im = -(as * tc) - ar * ts;
;             bf16_t* op = A1 + (sbase + (size_t)ka * 128 + b) * 2048 + cb * 128 + 16 * w + 4 * lq;
;             u32x2 o; o.x = cvt_pk_bf16(re[0], re[1]); o.y = cvt_pk_bf16(re[2], re[3]); *(u32x2*)op = o;
;             o.x = cvt_pk_bf16(im[0], im[1]); o.y = cvt_pk_bf16(im[2], im[3]); *(u32x2*)(op + 1024) = o; }
	v_mfma_f32_16x16x32_bf16 v[42:45], v[30:33], v[50:53], v[42:45]
	v_mul_f32_e64 v50, v48, 0.5
	v_mul_f32_e64 v51, v49, 0.5
	s_cmpk_gt_i32 s22, 0x7ff
	v_fract_f32_e32 v6, v51
	v_add_f32_e32 v6, v6, v6
	v_cmp_neq_f32_e64 s[0:1], s7, v51
	s_nop 1
	v_cndmask_b32_e64 v6, 0, v6, s[0:1]
	v_cmp_lt_f32_e64 s[0:1], 1.0, v49
	s_nop 1
	v_cndmask_b32_e64 v6, v49, v6, s[0:1]
	v_add_f32_e32 v51, v6, v6
	v_rndne_f32_e32 v51, v51
	v_fmac_f32_e32 v6, -0.5, v51
	v_mul_f32_e32 v52, v6, v6
	v_fmamk_f32 v53, v52, 0x3e75aa41, v58
	v_fmaak_f32 v53, v52, v53, 0x40234736
	v_fmaak_f32 v53, v52, v53, 0xc0a55e0e
	v_mul_f32_e32 v54, v6, v52
	v_mul_f32_e32 v53, v54, v53
	v_cvt_i32_f32_e32 v51, v51
	v_fmac_f32_e32 v53, 0x40490fdb, v6
	v_fmamk_f32 v6, v52, 0x3d4be544, v59
	v_fmaak_f32 v6, v52, v6, 0xbfaad1da
	v_fmaak_f32 v6, v52, v6, 0x4081e0d3
	v_fmaak_f32 v6, v52, v6, 0xc09de9e6
	v_fma_f32 v6, v52, v6, 1.0
	v_lshlrev_b32_e32 v52, 30, v51
	v_and_b32_e32 v51, 1, v51
	v_cmp_eq_u32_e64 s[0:1], 0, v51
	s_nop 1
	v_cndmask_b32_e64 v51, v6, v53, s[0:1]
	v_xor_b32_e32 v53, 0x80000000, v53
	v_bitop3_b32 v51, v51, v52, s10 bitop3:0x78
	v_cndmask_b32_e64 v6, v53, v6, s[0:1]
	v_cmp_lg_f32_e64 s[0:1], s7, v49
	v_bitop3_b32 v6, v6, v52, s10 bitop3:0x78
	s_nop 0
	v_cndmask_b32_e64 v52, v60, v51, s[0:1]
	v_cndmask_b32_e64 v6, v60, v6, s[0:1]
	v_pk_mul_f32 v[54:55], v[52:53], v[38:39] op_sel_hi:[0,1]
	v_pk_mul_f32 v[56:57], v[52:53], v[40:41] op_sel_hi:[0,1]
	v_pk_fma_f32 v[56:57], v[6:7], v[28:29], v[56:57] op_sel_hi:[0,1,1] neg_lo:[0,0,1] neg_hi:[0,0,1]
	v_pk_fma_f32 v[54:55], v[6:7], v[26:27], v[54:55] op_sel_hi:[0,1,1] neg_lo:[0,0,1] neg_hi:[0,0,1]
	v_pk_mul_f32 v[26:27], v[52:53], v[26:27] op_sel_hi:[0,1]
	v_pk_mul_f32 v[28:29], v[52:53], v[28:29] op_sel_hi:[0,1]
	v_pk_fma_f32 v[28:29], v[40:41], v[6:7], v[28:29] op_sel_hi:[1,0,1] neg_lo:[0,1,1] neg_hi:[0,1,1]
	v_pk_fma_f32 v[26:27], v[38:39], v[6:7], v[26:27] op_sel_hi:[1,0,1] neg_lo:[0,1,1] neg_hi:[0,1,1]
	v_fract_f32_e32 v6, v50
	v_add_f32_e32 v6, v6, v6
	v_cmp_neq_f32_e64 s[0:1], s7, v50
	v_cvt_pk_bf16_f32 v26, v26, v27
	v_cvt_pk_bf16_f32 v27, v28, v29
	v_cndmask_b32_e64 v6, 0, v6, s[0:1]
	v_cmp_lt_f32_e64 s[0:1], 1.0, v48
	ds_write_b64 v232, v[26:27] offset:17408
	v_cvt_pk_bf16_f32 v38, v54, v55
	v_cndmask_b32_e64 v6, v48, v6, s[0:1]
	v_add_f32_e32 v26, v6, v6
	v_rndne_f32_e32 v26, v26
	v_fmac_f32_e32 v6, -0.5, v26
	v_mul_f32_e32 v27, v6, v6
	v_fmamk_f32 v28, v27, 0x3e75aa41, v58
	v_fmaak_f32 v28, v27, v28, 0x40234736
	v_fmaak_f32 v28, v27, v28, 0xc0a55e0e
	v_mul_f32_e32 v29, v6, v27
	v_mul_f32_e32 v28, v29, v28
	v_cvt_i32_f32_e32 v26, v26
	v_fmac_f32_e32 v28, 0x40490fdb, v6
	v_fmamk_f32 v6, v27, 0x3d4be544, v59
	v_fmaak_f32 v6, v27, v6, 0xbfaad1da
	v_fmaak_f32 v6, v27, v6, 0x4081e0d3
	v_fmaak_f32 v6, v27, v6, 0xc09de9e6
	v_fma_f32 v6, v27, v6, 1.0
	v_lshlrev_b32_e32 v27, 30, v26
	v_and_b32_e32 v26, 1, v26
	v_cmp_eq_u32_e64 s[0:1], 0, v26
	v_cvt_pk_bf16_f32 v39, v56, v57
	ds_write_b64 v232, v[38:39] offset:0
	v_cndmask_b32_e64 v26, v6, v28, s[0:1]
	v_xor_b32_e32 v28, 0x80000000, v28
	v_bitop3_b32 v26, v26, v27, s10 bitop3:0x78
	v_cndmask_b32_e64 v6, v28, v6, s[0:1]
	v_cmp_lg_f32_e64 s[0:1], s7, v48
	v_bitop3_b32 v6, v6, v27, s10 bitop3:0x78
	s_nop 0
	v_cndmask_b32_e64 v26, v60, v26, s[0:1]
	v_cndmask_b32_e64 v6, v60, v6, s[0:1]
	v_pk_mul_f32 v[28:29], v[26:27], v[42:43] op_sel_hi:[0,1]
	v_pk_mul_f32 v[38:39], v[26:27], v[44:45] op_sel_hi:[0,1]
	v_pk_fma_f32 v[48:49], v[6:7], v[34:35], v[28:29] op_sel_hi:[0,1,1] neg_lo:[0,0,1] neg_hi:[0,0,1]
	v_pk_mul_f32 v[34:35], v[26:27], v[34:35] op_sel_hi:[0,1]
	v_pk_mul_f32 v[26:27], v[26:27], v[36:37] op_sel_hi:[0,1]
	v_pk_fma_f32 v[50:51], v[44:45], v[6:7], v[26:27] op_sel_hi:[1,0,1] neg_lo:[0,1,1] neg_hi:[0,1,1]
	ds_read_b128 v[26:29], v11
	v_pk_fma_f32 v[46:47], v[6:7], v[36:37], v[38:39] op_sel_hi:[0,1,1] neg_lo:[0,0,1] neg_hi:[0,0,1]
	v_pk_fma_f32 v[52:53], v[42:43], v[6:7], v[34:35] op_sel_hi:[1,0,1] neg_lo:[0,1,1] neg_hi:[0,1,1]
	ds_read_b128 v[34:37], v11 offset:9216
	ds_read_b128 v[38:41], v11 offset:64
	v_or_b32_e32 v6, s23, v10
	s_waitcnt lgkmcnt(2)
	v_mfma_f32_16x16x32_bf16 v[26:29], v[22:25], v[26:29], 0
	ds_read_b128 v[42:45], v11 offset:9280
	v_or_b32_e32 v6, s6, v6
	v_lshlrev_b64 v[54:55], 12, v[6:7]
	s_waitcnt lgkmcnt(2)
	v_mfma_f32_16x16x32_bf16 v[34:37], v[22:25], v[34:37], 0
	v_lshl_add_u64 v[54:55], v[4:5], 0, v[54:55]
	v_cvt_pk_bf16_f32 v48, v48, v49
	v_cvt_pk_bf16_f32 v49, v46, v47
	s_waitcnt lgkmcnt(1)
	v_mfma_f32_16x16x32_bf16 v[26:29], v[30:33], v[38:41], v[26:29]
	ds_write_b64 v232, v[48:49] offset:4352
	ds_read_b128 v[38:41], v13
	v_cvt_pk_bf16_f32 v52, v52, v53
	s_waitcnt lgkmcnt(1)
	v_mfma_f32_16x16x32_bf16 v[34:37], v[30:33], v[42:45], v[34:37]
	ds_read_b128 v[42:45], v13 offset:9216
	ds_read_b128 v[46:49], v13 offset:64
	v_cvt_pk_bf16_f32 v53, v50, v51
	ds_write_b64 v232, v[52:53] offset:21760
	s_waitcnt lgkmcnt(2)
	v_mfma_f32_16x16x32_bf16 v[38:41], v[22:25], v[38:41], 0
	v_mul_u32_u24_e32 v54, s23, v17
	ds_read_b128 v[50:53], v13 offset:9280
	v_or_b32_e32 v6, s23, v12
	s_waitcnt lgkmcnt(2)
	v_mfma_f32_16x16x32_bf16 v[22:25], v[22:25], v[42:45], 0
	v_mul_u32_u24_e32 v42, s23, v18
	v_cvt_f32_u32_e32 v43, v42
	v_cvt_f32_u32_e32 v42, v54
	s_waitcnt lgkmcnt(1)
	v_mfma_f32_16x16x32_bf16 v[38:41], v[30:33], v[46:49], v[38:41]
	v_or_b32_e32 v6, s6, v6
	v_lshlrev_b64 v[44:45], 12, v[6:7]
	v_lshl_add_u64 v[44:45], v[4:5], 0, v[44:45]
	s_waitcnt lgkmcnt(0)
; __device__ __forceinline__ unsigned cvt_pk_bf16(float lo, float hi) { const f2_t v = {lo, hi}; const bf2_t b = __builtin_convertvector(v, bf2_t); return __builtin_bit_cast(unsigned, b); }
; __device__ __forceinline__ f32x4 mfma16(bf16x8 a, bf16x8 b, f32x4 c) { return __builtin_amdgcn_mfma_f32_16x16x32_bf16(a, b, c, 0, 0, 0); }
; template <int N1> __device__ void fft1_units(int wv, const Params& p, unsigned char* lds, int seq_lo, int nseq, int part, int nparts) {
;     ...
;     for (int unit = part; unit < nunits; unit += nparts) {
;         const int sq = unit / 1024, b = (unit >> 3) & 127, cb = unit & 7;
;         const int seq = seq_lo + sq; const size_t sbase = (size_t)seq * 8192;
;         for (int idx = tid; idx < N1 * 16; idx += NTHR) { const int a = idx % N1, c8 = (idx / N1) * 8;
;             const bf16x8 v = *(const bf16x8*)(z + (sbase + 128 * a + b) * DM + cb * 128 + c8);
;     ...
;         for (int i = 0; i < NB; ++i) { f32x4 ar = {0, 0, 0, 0}, as = {0, 0, 0, 0};
; #pragma unroll
;             for (int kk = 0; kk < NK; ++kk) { const bf16x8 cf = *(const bf16x8*)(CT + (16 * i + lr) * PW + 32 * kk + 8 * lq), sf = *(const bf16x8*)(ST + (16 * i + lr) * PW + 32 * kk + 8 * lq);
;                 ar = mfma16(xf[kk], cf, ar); as = mfma16(xf[kk], sf, as); }
;             const int ka = 16 * i + lr; float tc, ts; sincospif(2.0f * (float)(b * ka) / (float)S, &ts, &tc);
;             const f32x4 re = ar * tc - as * ts, im = -(as * tc) - ar * ts;
;             bf16_t* op = A1 + (sbase + (size_t)ka * 128 + b) * 2048 + cb * 128 + 16 * w + 4 * lq;
;             u32x2 o; o.x = cvt_pk_bf16(re[0], re[1]); o.y = cvt_pk_bf16(re[2], re[3]); *(u32x2*)op = o;
;             o.x = cvt_pk_bf16(im[0], im[1]); o.y = cvt_pk_bf16(im[2], im[3]); *(u32x2*)(op + 1024) = o; }
;         __syncthreads();
	v_mfma_f32_16x16x32_bf16 v[22:25], v[30:33], v[50:53], v[22:25]
	v_mul_f32_e64 v30, v42, s14
	v_mul_f32_e64 v31, v43, s14
	v_pk_mul_f32 v[32:33], v[30:31], 0.5 op_sel_hi:[1,0]
	s_nop 0
	v_fract_f32_e32 v6, v33
	v_add_f32_e32 v6, v6, v6
	v_cmp_neq_f32_e64 s[0:1], s7, v33
	s_nop 1
	v_cndmask_b32_e64 v6, 0, v6, s[0:1]
	v_cmp_lt_f32_e64 s[0:1], 1.0, v31
	s_nop 1
	v_cndmask_b32_e64 v6, v31, v6, s[0:1]
	v_add_f32_e32 v33, v6, v6
	v_rndne_f32_e32 v33, v33
	v_fmac_f32_e32 v6, -0.5, v33
	v_mul_f32_e32 v42, v6, v6
	v_fmamk_f32 v43, v42, 0x3e75aa41, v58
	v_fmaak_f32 v43, v42, v43, 0x40234736
	v_fmaak_f32 v43, v42, v43, 0xc0a55e0e
	v_mul_f32_e32 v46, v6, v42
	v_mul_f32_e32 v43, v46, v43
	v_cvt_i32_f32_e32 v33, v33
	v_fmac_f32_e32 v43, 0x40490fdb, v6
	v_fmamk_f32 v6, v42, 0x3d4be544, v59
	v_fmaak_f32 v6, v42, v6, 0xbfaad1da
	v_fmaak_f32 v6, v42, v6, 0x4081e0d3
	v_fmaak_f32 v6, v42, v6, 0xc09de9e6
	v_fma_f32 v6, v42, v6, 1.0
	v_lshlrev_b32_e32 v42, 30, v33
	v_and_b32_e32 v33, 1, v33
	v_cmp_eq_u32_e64 s[0:1], 0, v33
	s_nop 1
	v_cndmask_b32_e64 v33, v6, v43, s[0:1]
	v_xor_b32_e32 v43, 0x80000000, v43
	v_bitop3_b32 v33, v33, v42, s10 bitop3:0x78
	v_cndmask_b32_e64 v6, v43, v6, s[0:1]
	v_cmp_lg_f32_e64 s[0:1], s7, v31
	v_bitop3_b32 v6, v6, v42, s10 bitop3:0x78
	s_nop 0
	v_cndmask_b32_e64 v42, v60, v33, s[0:1]
	v_cndmask_b32_e64 v6, v60, v6, s[0:1]
	v_pk_mul_f32 v[46:47], v[42:43], v[34:35] op_sel_hi:[0,1]
	v_pk_mul_f32 v[48:49], v[42:43], v[36:37] op_sel_hi:[0,1]
	v_pk_fma_f32 v[48:49], v[6:7], v[28:29], v[48:49] op_sel_hi:[0,1,1] neg_lo:[0,0,1] neg_hi:[0,0,1]
	v_pk_fma_f32 v[46:47], v[6:7], v[26:27], v[46:47] op_sel_hi:[0,1,1] neg_lo:[0,0,1] neg_hi:[0,0,1]
	v_pk_mul_f32 v[26:27], v[42:43], v[26:27] op_sel_hi:[0,1]
	v_pk_mul_f32 v[28:29], v[42:43], v[28:29] op_sel_hi:[0,1]
	v_pk_fma_f32 v[28:29], v[36:37], v[6:7], v[28:29] op_sel_hi:[1,0,1] neg_lo:[0,1,1] neg_hi:[0,1,1]
	v_pk_fma_f32 v[26:27], v[34:35], v[6:7], v[26:27] op_sel_hi:[1,0,1] neg_lo:[0,1,1] neg_hi:[0,1,1]
	v_fract_f32_e32 v6, v32
	v_add_f32_e32 v6, v6, v6
	v_cmp_neq_f32_e64 s[0:1], s7, v32
	v_cvt_pk_bf16_f32 v26, v26, v27
	v_cvt_pk_bf16_f32 v27, v28, v29
	v_cndmask_b32_e64 v6, 0, v6, s[0:1]
	v_cmp_lt_f32_e64 s[0:1], 1.0, v30
	ds_write_b64 v232, v[26:27] offset:26112
	v_cvt_pk_bf16_f32 v34, v46, v47
	v_cndmask_b32_e64 v6, v30, v6, s[0:1]
	v_add_f32_e32 v26, v6, v6
	v_rndne_f32_e32 v26, v26
	v_fmac_f32_e32 v6, -0.5, v26
	v_mul_f32_e32 v27, v6, v6
	v_fmamk_f32 v28, v27, 0x3e75aa41, v58
	v_fmaak_f32 v28, v27, v28, 0x40234736
	v_fmaak_f32 v28, v27, v28, 0xc0a55e0e
	v_mul_f32_e32 v29, v6, v27
	v_mul_f32_e32 v28, v29, v28
	v_cvt_i32_f32_e32 v26, v26
	v_fmac_f32_e32 v28, 0x40490fdb, v6
	v_fmamk_f32 v6, v27, 0x3d4be544, v59
	v_fmaak_f32 v6, v27, v6, 0xbfaad1da
	v_fmaak_f32 v6, v27, v6, 0x4081e0d3
	v_fmaak_f32 v6, v27, v6, 0xc09de9e6
	v_fma_f32 v6, v27, v6, 1.0
	v_lshlrev_b32_e32 v27, 30, v26
	v_and_b32_e32 v26, 1, v26
	v_cmp_eq_u32_e64 s[0:1], 0, v26
	v_cvt_pk_bf16_f32 v35, v48, v49
	ds_write_b64 v232, v[34:35] offset:8704
	v_cndmask_b32_e64 v26, v6, v28, s[0:1]
	v_xor_b32_e32 v28, 0x80000000, v28
	v_bitop3_b32 v26, v26, v27, s10 bitop3:0x78
	v_cndmask_b32_e64 v6, v28, v6, s[0:1]
	v_cmp_lg_f32_e64 s[0:1], s7, v30
	v_bitop3_b32 v6, v6, v27, s10 bitop3:0x78
	s_nop 0
	v_cndmask_b32_e64 v26, v60, v26, s[0:1]
	v_cndmask_b32_e64 v6, v60, v6, s[0:1]
	v_pk_mul_f32 v[28:29], v[26:27], v[22:23] op_sel_hi:[0,1]
	v_pk_mul_f32 v[30:31], v[26:27], v[24:25] op_sel_hi:[0,1]
	v_pk_mul_f32 v[32:33], v[26:27], v[38:39] op_sel_hi:[0,1]
	v_pk_mul_f32 v[26:27], v[26:27], v[40:41] op_sel_hi:[0,1]
	v_pk_fma_f32 v[30:31], v[6:7], v[40:41], v[30:31] op_sel_hi:[0,1,1] neg_lo:[0,0,1] neg_hi:[0,0,1]
	v_pk_fma_f32 v[28:29], v[6:7], v[38:39], v[28:29] op_sel_hi:[0,1,1] neg_lo:[0,0,1] neg_hi:[0,0,1]
	v_pk_fma_f32 v[24:25], v[24:25], v[6:7], v[26:27] op_sel_hi:[1,0,1] neg_lo:[0,1,1] neg_hi:[0,1,1]
	v_pk_fma_f32 v[22:23], v[22:23], v[6:7], v[32:33] op_sel_hi:[1,0,1] neg_lo:[0,1,1] neg_hi:[0,1,1]
	v_or_b32_e32 v6, s23, v14
	v_or_b32_e32 v6, s6, v6
	v_lshlrev_b64 v[6:7], 12, v[6:7]
	v_lshl_add_u64 v[4:5], v[4:5], 0, v[6:7]
	v_cvt_pk_bf16_f32 v6, v28, v29
	v_cvt_pk_bf16_f32 v7, v30, v31
	ds_write_b64 v232, v[6:7] offset:13056
	v_cvt_pk_bf16_f32 v6, v22, v23
	v_cvt_pk_bf16_f32 v7, v24, v25
	ds_write_b64 v232, v[6:7] offset:30464
	s_waitcnt lgkmcnt(0)
	s_barrier
	ds_read_b128 v[100:103], v233 offset:0
	ds_read_b128 v[104:107], v233 offset:17408
	ds_read_b128 v[108:111], v233 offset:8704
	ds_read_b128 v[112:115], v233 offset:26112
	s_mov_b64 s[14:15], 0x1000000
	v_mov_b32_e32 v236, v242
	v_mov_b32_e32 v237, v243
	s_waitcnt lgkmcnt(3)
	global_store_dwordx4 v[236:237], v[100:103], off
	s_waitcnt lgkmcnt(2)
	global_store_dwordx4 v[236:237], v[104:107], off offset:2048
	v_lshl_add_u64 v[236:237], v[236:237], 0, s[14:15]
	s_waitcnt lgkmcnt(1)
	global_store_dwordx4 v[236:237], v[108:111], off
	s_waitcnt lgkmcnt(0)
	global_store_dwordx4 v[236:237], v[112:115], off offset:2048
	s_barrier
	s_cmpk_gt_i32 s22, 0x7ff
	s_cbranch_scc1 .LBB0_333
.LBB0_327:
	s_and_b32 s16, s22, 7
	s_lshl_b32 s36, s16, 7
	s_ashr_i32 s0, s22, 31
	s_lshr_b32 s0, s0, 22
	s_add_i32 s0, s22, s0
	s_ashr_i32 s0, s0, 10
	s_ashr_i32 s1, s0, 31
	s_bfe_u32 s23, s22, 0x70003
	s_lshl_b64 s[6:7], s[0:1], 13
	s_mov_b64 s[10:11], exec
	v_mov_b64_e32 v[4:5], s[36:37]
	s_or_b32 s14, s6, s23
	s_mov_b32 s15, s7
	s_lshl_b32 s0, s16, 8
	s_lshl_b64 s[20:21], s[14:15], 12
	s_add_u32 s20, s20, s0
	s_addc_u32 s21, s21, 0
	v_lshl_add_u64 v[242:243], s[20:21], 0, v[244:245]
	s_add_u32 s16, s76, s0
	s_addc_u32 s17, s77, 0
	s_lshl_b64 s[14:15], s[14:15], 11
	s_add_u32 s14, s14, s16
	s_addc_u32 s15, s15, s17
	v_lshl_add_u64 v[204:205], s[14:15], 0, v[200:201]
	s_mov_b64 s[16:17], 0x800000
	global_load_dwordx4 v[206:209], v[204:205], off
	v_lshl_add_u64 v[204:205], v[204:205], 0, s[16:17]
	global_load_dwordx4 v[210:213], v[204:205], off
	s_waitcnt vmcnt(1)
	ds_write_b128 v202, v[206:209]
	s_waitcnt vmcnt(0)
	ds_write_b128 v202, v[210:213] offset:8192
	s_branch .LBB0_326
